# skip the grid barrier between out-projection(g) and in-projection(g+1) (no data dependency); residual-epilogue stores without nt
# speedup vs baseline: 1.0066x; 1.0006x over previous
.LBB0_1114:
	s_lshl_b32 s12, s65, 8
	s_add_i32 s13, s56, s12
	s_add_i32 s14, s13, 0xffff8000
	s_lshr_b32 s14, s14, 13
	s_ashr_i32 s12, s13, 14
	s_add_i32 s14, s14, 2
	s_cmp_lt_i32 s13, 0x8000
	s_cselect_b32 s14, s12, s14
	s_ashr_i32 s15, s14, 31
	s_mul_i32 s16, s14, 0x12000
	s_mul_hi_i32 s12, s14, 0x12000
	s_add_u32 s16, s54, s16
	s_addc_u32 s17, s55, s12
	s_ashr_i32 s22, s13, 5
	s_lshl_b32 s12, s64, 8
	s_add_i32 s22, s22, s64
	s_or_b32 s12, s12, s59
	s_ashr_i32 s23, s22, 31
	v_or_b32_e32 v162, s12, v203
	s_lshl_b64 s[22:23], s[22:23], 18
	s_lshl_b64 s[14:15], s[14:15], 13
	v_ashrrev_i32_e32 v163, 31, v162
	s_add_u32 s14, s57, s14
	v_lshlrev_b64 v[42:43], 2, v[162:163]
	s_addc_u32 s15, s58, s15
	v_lshl_add_u64 v[44:45], s[16:17], 0, v[42:43]
	v_lshl_add_u64 v[48:49], s[14:15], 0, v[42:43]
	s_mov_b32 s14, 0x10a000
	v_add_co_u32_e32 v42, vcc, s14, v44
	s_mov_b64 s[16:17], 0x10a000
	s_nop 0
	v_addc_co_u32_e32 v43, vcc, 0, v45, vcc
	v_lshl_add_u64 v[194:195], v[190:191], 0, s[22:23]
	v_lshl_add_u64 v[46:47], v[44:45], 0, s[16:17]
	v_add_co_u32_e32 v196, vcc, s11, v194
	global_load_dwordx4 v[78:81], v[42:43], off
	global_load_dwordx4 v[74:77], v[46:47], off offset:16
	global_load_dwordx4 v[66:69], v[48:49], off offset:16
	global_load_dwordx4 v[70:73], v[48:49], off
	global_load_dwordx4 v[50:53], v[46:47], off offset:528
	global_load_dwordx4 v[54:57], v[46:47], off offset:512
	global_load_dwordx4 v[42:45], v[48:49], off offset:528
	s_nop 0
	global_load_dwordx4 v[46:49], v[48:49], off offset:512
	v_addc_co_u32_e32 v197, vcc, 0, v195, vcc
	global_load_dwordx4 v[212:215], v[194:195], off
	global_load_dwordx4 v[216:219], v[196:197], off
	v_add_co_u32_e32 v198, vcc, s29, v194
	v_add_u32_e32 v192, s13, v202
	s_nop 0
	v_addc_co_u32_e32 v199, vcc, 0, v195, vcc
	global_load_dwordx4 v[182:185], v[198:199], off
	s_movk_i32 s13, 0x6000
	v_add_co_u32_e32 v200, vcc, s13, v194
	s_mov_b32 s13, 0x8000
	s_nop 0
	v_addc_co_u32_e32 v201, vcc, 0, v195, vcc
	global_load_dwordx4 v[178:181], v[200:201], off
	v_lshlrev_b32_e32 v0, 1, v162
	v_add_co_u32_e32 v162, vcc, s13, v194
	s_mov_b32 s13, 0xa000
	s_nop 0
	v_addc_co_u32_e32 v163, vcc, 0, v195, vcc
	global_load_dwordx4 v[174:177], v[162:163], off
	v_add_co_u32_e32 v162, vcc, s13, v194
	s_mov_b32 s13, 0xc000
	s_nop 0
	v_addc_co_u32_e32 v163, vcc, 0, v195, vcc
	global_load_dwordx4 v[170:173], v[162:163], off
	v_add_co_u32_e32 v162, vcc, s13, v194
	s_mov_b32 s13, 0xe000
	s_nop 0
	v_addc_co_u32_e32 v163, vcc, 0, v195, vcc
	global_load_dwordx4 v[166:169], v[162:163], off
	v_add_co_u32_e32 v162, vcc, s13, v194
	s_ashr_i32 s15, s12, 6
	s_nop 0
	v_addc_co_u32_e32 v163, vcc, 0, v195, vcc
	global_load_dwordx4 v[162:165], v[162:163], off
	s_bfe_u32 s14, s59, 0x10005
	v_and_b32_e32 v206, 48, v0
	v_lshlrev_b32_e32 v0, 6, v192
	s_or_b32 s13, s63, s14
	v_and_or_b32 v207, v0, s82, v206
	v_lshlrev_b32_e32 v0, 2, v192
	s_lshl_b32 s17, s13, 10
	s_or_b32 s16, s15, 2
	v_ashrrev_i32_e32 v193, 31, v192
	s_waitcnt vmcnt(0)
	v_pk_fma_f32 v[160:161], v[160:161], v[80:81], v[214:215]
	v_pk_fma_f32 v[158:159], v[158:159], v[78:79], v[212:213]
	v_pk_fma_f32 v[156:157], v[156:157], v[76:77], v[218:219]
	v_pk_fma_f32 v[154:155], v[154:155], v[74:75], v[216:217]
	global_store_dwordx4 v[194:195], v[158:161], off
	global_store_dwordx4 v[196:197], v[154:157], off
	v_ashrrev_i32_e32 v196, 3, v192
	v_and_b32_e32 v213, 0xffffffe0, v196
	v_pk_mul_f32 v[196:197], v[72:73], v[160:161]
	v_pk_mul_f32 v[208:209], v[70:71], v[158:159]
	v_cvt_pk_bf16_f32 v215, v196, v197
	v_add_u32_e32 v196, s15, v213
	v_pk_mul_f32 v[216:217], v[66:67], v[154:155]
	v_ashrrev_i32_e32 v197, 31, v196
	v_mul_f32_e32 v159, v159, v159
	v_mul_f32_e32 v155, v155, v155
	v_and_b32_e32 v212, 32, v0
	v_lshlrev_b64 v[196:197], 15, v[196:197]
	v_fmac_f32_e32 v159, v158, v158
	v_mul_f32_e32 v158, v161, v161
	v_fmac_f32_e32 v155, v154, v154
	v_mul_f32_e32 v154, v157, v157
	v_bitop3_b32 v0, v207, s17, v212 bitop3:0xde
	v_pk_mul_f32 v[210:211], v[68:69], v[156:157]
	v_lshl_add_u64 v[196:197], s[26:27], 0, v[196:197]
	v_fmac_f32_e32 v158, v160, v160
	v_fmac_f32_e32 v154, v156, v156
	v_cvt_pk_bf16_f32 v214, v208, v209
	v_cvt_pk_bf16_f32 v216, v216, v217
	v_cvt_pk_bf16_f32 v217, v210, v211
	v_lshl_add_u64 v[208:209], v[196:197], 0, v[0:1]
	v_add_f32_e32 v158, v159, v158
	v_add_f32_e32 v154, v155, v154
	v_pk_fma_f32 v[152:153], v[152:153], v[56:57], v[184:185]
	global_store_dwordx4 v[208:209], v[214:217], off
	v_add_f32_e32 v208, v158, v154
	v_pk_mul_f32 v[154:155], v[48:49], v[152:153]
	v_pk_fma_f32 v[150:151], v[150:151], v[54:55], v[182:183]
	v_cvt_pk_bf16_f32 v159, v154, v155
	v_add_u32_e32 v154, s16, v213
	v_ashrrev_i32_e32 v155, 31, v154
	v_pk_mul_f32 v[156:157], v[46:47], v[150:151]
	v_lshlrev_b64 v[154:155], 15, v[154:155]
	v_pk_fma_f32 v[146:147], v[146:147], v[50:51], v[178:179]
	v_cvt_pk_bf16_f32 v158, v156, v157
	v_lshl_add_u64 v[156:157], s[26:27], 0, v[154:155]
	v_pk_fma_f32 v[148:149], v[148:149], v[52:53], v[180:181]
	global_store_dwordx4 v[198:199], v[150:153], off
	global_store_dwordx4 v[200:201], v[146:149], off
	v_pk_mul_f32 v[160:161], v[42:43], v[146:147]
	v_lshl_add_u64 v[154:155], v[156:157], 0, v[0:1]
	v_mul_f32_e32 v0, v151, v151
	v_mul_f32_e32 v147, v147, v147
	v_fmac_f32_e32 v0, v150, v150
	v_mul_f32_e32 v150, v153, v153
	v_fmac_f32_e32 v147, v146, v146
	v_mul_f32_e32 v146, v149, v149
	v_fmac_f32_e32 v150, v152, v152
	v_fmac_f32_e32 v146, v148, v148
	v_add_f32_e32 v0, v0, v150
	v_add_f32_e32 v146, v147, v146
	v_add_f32_e32 v0, v0, v146
	v_add_f32_e32 v0, v208, v0
	ds_swizzle_b32 v146, v0 offset:swizzle(SWAP,16)
	v_pk_mul_f32 v[178:179], v[44:45], v[148:149]
	v_cvt_pk_bf16_f32 v160, v160, v161
	v_cvt_pk_bf16_f32 v161, v178, v179
	global_store_dwordx4 v[154:155], v[158:161], off
	s_waitcnt lgkmcnt(0)
	v_add_f32_e32 v0, v0, v146
	v_mov_b32_e32 v146, v0
	s_nop 1
	v_permlane32_swap_b32_e32 v0, v146
	v_lshl_add_u64 v[154:155], v[192:193], 2, s[6:7]
	s_and_saveexec_b64 s[12:13], s[36:37]
	s_cbranch_execz .LBB0_1116
	v_add_f32_e32 v0, v0, v146
	global_atomic_add_f32 v[154:155], v0, off
.LBB0_1116:
	s_or_b64 exec, exec, s[12:13]
	s_mov_b64 s[12:13], 0x8000
	v_or_b32_e32 v0, 16, v192
	v_lshl_add_u64 v[146:147], v[194:195], 0, s[12:13]
	s_mov_b64 s[12:13], 0xa000
	v_pk_fma_f32 v[144:145], v[144:145], v[80:81], v[176:177]
	v_pk_fma_f32 v[142:143], v[142:143], v[78:79], v[174:175]
	v_pk_fma_f32 v[138:139], v[138:139], v[74:75], v[170:171]
	v_lshrrev_b32_e32 v0, 3, v0
	v_lshl_add_u64 v[148:149], v[194:195], 0, s[12:13]
	v_pk_fma_f32 v[140:141], v[140:141], v[76:77], v[172:173]
	global_store_dwordx4 v[146:147], v[142:145], off
	global_store_dwordx4 v[148:149], v[138:141], off
	v_and_or_b32 v0, v0, 10, s14
	v_pk_mul_f32 v[146:147], v[70:71], v[142:143]
	v_pk_mul_f32 v[160:161], v[66:67], v[138:139]
	v_mul_f32_e32 v143, v143, v143
	v_mul_f32_e32 v139, v139, v139
	v_lshlrev_b32_e32 v0, 10, v0
	v_fmac_f32_e32 v143, v142, v142
	v_mul_f32_e32 v142, v145, v145
	v_fmac_f32_e32 v139, v138, v138
	v_mul_f32_e32 v138, v141, v141
	s_mov_b64 s[12:13], 0xc000
	v_bitop3_b32 v0, v207, v0, v212 bitop3:0xde
	v_pk_mul_f32 v[148:149], v[72:73], v[144:145]
	v_pk_mul_f32 v[158:159], v[68:69], v[140:141]
	v_fmac_f32_e32 v142, v144, v144
	v_fmac_f32_e32 v138, v140, v140
	v_lshl_add_u64 v[150:151], v[194:195], 0, s[12:13]
	s_mov_b64 s[12:13], 0xe000
	v_cvt_pk_bf16_f32 v146, v146, v147
	v_cvt_pk_bf16_f32 v147, v148, v149
	v_cvt_pk_bf16_f32 v148, v160, v161
	v_cvt_pk_bf16_f32 v149, v158, v159
	v_lshl_add_u64 v[158:159], v[196:197], 0, v[0:1]
	v_add_f32_e32 v142, v143, v142
	v_add_f32_e32 v138, v139, v138
	v_pk_fma_f32 v[136:137], v[136:137], v[56:57], v[168:169]
	v_pk_fma_f32 v[134:135], v[134:135], v[54:55], v[166:167]
	v_pk_fma_f32 v[130:131], v[130:131], v[50:51], v[162:163]
	v_lshl_add_u64 v[152:153], v[194:195], 0, s[12:13]
	global_store_dwordx4 v[158:159], v[146:149], off
	v_pk_fma_f32 v[132:133], v[132:133], v[52:53], v[164:165]
	global_store_dwordx4 v[150:151], v[134:137], off
	global_store_dwordx4 v[152:153], v[130:133], off
	v_add_f32_e32 v146, v142, v138
	v_pk_mul_f32 v[138:139], v[46:47], v[134:135]
	v_pk_mul_f32 v[144:145], v[42:43], v[130:131]
	v_mul_f32_e32 v135, v135, v135
	v_mul_f32_e32 v131, v131, v131
	v_fmac_f32_e32 v135, v134, v134
	v_mul_f32_e32 v134, v137, v137
	v_fmac_f32_e32 v131, v130, v130
	v_mul_f32_e32 v130, v133, v133
	v_fmac_f32_e32 v134, v136, v136
	v_fmac_f32_e32 v130, v132, v132
	v_add_f32_e32 v134, v135, v134
	v_add_f32_e32 v130, v131, v130
	v_add_f32_e32 v130, v134, v130
	v_pk_mul_f32 v[142:143], v[44:45], v[132:133]
	v_add_f32_e32 v132, v146, v130
	ds_swizzle_b32 v133, v132 offset:swizzle(SWAP,16)
	v_pk_mul_f32 v[140:141], v[48:49], v[136:137]
	v_cvt_pk_bf16_f32 v138, v138, v139
	v_cvt_pk_bf16_f32 v139, v140, v141
	v_cvt_pk_bf16_f32 v140, v144, v145
	v_cvt_pk_bf16_f32 v141, v142, v143
	v_lshl_add_u64 v[130:131], v[156:157], 0, v[0:1]
	s_waitcnt lgkmcnt(0)
	v_add_f32_e32 v0, v132, v133
	global_store_dwordx4 v[130:131], v[138:141], off
	v_mov_b32_e32 v130, v0
	s_nop 1
	v_permlane32_swap_b32_e32 v0, v130
	s_and_saveexec_b64 s[12:13], s[36:37]
	s_cbranch_execz .LBB0_1118
	v_add_f32_e32 v0, v0, v130
	global_atomic_add_f32 v[154:155], v0, off offset:64
.LBB0_1118:
	s_or_b64 exec, exec, s[12:13]
	v_add_co_u32_e32 v170, vcc, 0x10000, v194
	v_or_b32_e32 v0, 32, v192
	s_nop 0
	v_addc_co_u32_e32 v171, vcc, 0, v195, vcc
	v_add_co_u32_e32 v172, vcc, 0x12000, v194
	global_load_dwordx4 v[162:165], v[170:171], off
	s_nop 0
	v_addc_co_u32_e32 v173, vcc, 0, v195, vcc
	global_load_dwordx4 v[166:169], v[172:173], off
	v_add_co_u32_e32 v158, vcc, 0x14000, v194
	v_lshrrev_b32_e32 v0, 3, v0
	s_nop 0
	v_addc_co_u32_e32 v159, vcc, 0, v195, vcc
	v_add_co_u32_e32 v160, vcc, 0x16000, v194
	global_load_dwordx4 v[150:153], v[158:159], off
	s_nop 0
	v_addc_co_u32_e32 v161, vcc, 0, v195, vcc
	global_load_dwordx4 v[146:149], v[160:161], off
	v_add_co_u32_e32 v130, vcc, 0x18000, v194
	v_and_or_b32 v0, v0, 12, s14
	s_nop 0
	v_addc_co_u32_e32 v131, vcc, 0, v195, vcc
	global_load_dwordx4 v[134:137], v[130:131], off
	v_add_co_u32_e32 v130, vcc, 0x1a000, v194
	v_lshlrev_b32_e32 v0, 10, v0
	s_nop 0
	v_addc_co_u32_e32 v131, vcc, 0, v195, vcc
	global_load_dwordx4 v[142:145], v[130:131], off
	v_add_co_u32_e32 v130, vcc, 0x1c000, v194
	s_waitcnt vmcnt(5)
	v_pk_fma_f32 v[126:127], v[126:127], v[78:79], v[162:163]
	v_addc_co_u32_e32 v131, vcc, 0, v195, vcc
	v_add_co_u32_e32 v138, vcc, 0x1e000, v194
	global_load_dwordx4 v[130:133], v[130:131], off
	s_nop 0
	v_addc_co_u32_e32 v139, vcc, 0, v195, vcc
	global_load_dwordx4 v[138:141], v[138:139], off
	s_waitcnt vmcnt(6)
	v_pk_fma_f32 v[162:163], v[122:123], v[74:75], v[166:167]
	v_lshlrev_b32_e32 v122, 6, v192
	v_lshlrev_b32_e32 v123, 2, v192
	v_pk_fma_f32 v[128:129], v[128:129], v[80:81], v[164:165]
	v_pk_fma_f32 v[164:165], v[124:125], v[76:77], v[168:169]
	v_and_or_b32 v122, v122, s82, v206
	v_and_b32_e32 v123, 32, v123
	global_store_dwordx4 v[170:171], v[126:129], off
	global_store_dwordx4 v[172:173], v[162:165], off
	v_bitop3_b32 v0, v122, v0, v123 bitop3:0xde
	v_pk_mul_f32 v[124:125], v[72:73], v[128:129]
	v_pk_mul_f32 v[166:167], v[70:71], v[126:127]
	v_pk_mul_f32 v[170:171], v[68:69], v[164:165]
	v_pk_mul_f32 v[168:169], v[66:67], v[162:163]
	v_cvt_pk_bf16_f32 v166, v166, v167
	v_cvt_pk_bf16_f32 v167, v124, v125
	v_cvt_pk_bf16_f32 v168, v168, v169
	v_cvt_pk_bf16_f32 v169, v170, v171
	v_lshl_add_u64 v[124:125], v[196:197], 0, v[0:1]
	global_store_dwordx4 v[124:125], v[166:169], off
	v_mul_f32_e32 v124, v127, v127
	v_mul_f32_e32 v125, v129, v129
	v_fmac_f32_e32 v124, v126, v126
	v_fmac_f32_e32 v125, v128, v128
	v_add_f32_e32 v124, v124, v125
	v_mul_f32_e32 v125, v163, v163
	v_mul_f32_e32 v126, v165, v165
	v_fmac_f32_e32 v125, v162, v162
	v_fmac_f32_e32 v126, v164, v164
	v_add_f32_e32 v125, v125, v126
	s_waitcnt vmcnt(8)
	v_pk_fma_f32 v[120:121], v[120:121], v[56:57], v[152:153]
	v_pk_fma_f32 v[118:119], v[118:119], v[54:55], v[150:151]
	s_waitcnt vmcnt(7)
	v_pk_fma_f32 v[116:117], v[116:117], v[52:53], v[148:149]
	v_add_f32_e32 v162, v124, v125
	v_pk_fma_f32 v[114:115], v[114:115], v[50:51], v[146:147]
	v_pk_mul_f32 v[126:127], v[48:49], v[120:121]
	v_pk_mul_f32 v[124:125], v[46:47], v[118:119]
	v_pk_mul_f32 v[128:129], v[44:45], v[116:117]
	global_store_dwordx4 v[158:159], v[118:121], off
	global_store_dwordx4 v[160:161], v[114:117], off
	v_pk_mul_f32 v[146:147], v[42:43], v[114:115]
	v_cvt_pk_bf16_f32 v124, v124, v125
	v_cvt_pk_bf16_f32 v125, v126, v127
	v_cvt_pk_bf16_f32 v127, v128, v129
	v_lshl_add_u64 v[128:129], v[156:157], 0, v[0:1]
	v_mul_f32_e32 v0, v119, v119
	v_mul_f32_e32 v115, v115, v115
	v_fmac_f32_e32 v0, v118, v118
	v_mul_f32_e32 v118, v121, v121
	v_fmac_f32_e32 v115, v114, v114
	v_mul_f32_e32 v114, v117, v117
	v_fmac_f32_e32 v118, v120, v120
	v_fmac_f32_e32 v114, v116, v116
	v_add_f32_e32 v0, v0, v118
	v_add_f32_e32 v114, v115, v114
	v_add_f32_e32 v0, v0, v114
	v_add_f32_e32 v0, v162, v0
	ds_swizzle_b32 v114, v0 offset:swizzle(SWAP,16)
	v_cvt_pk_bf16_f32 v126, v146, v147
	global_store_dwordx4 v[128:129], v[124:127], off
	s_waitcnt lgkmcnt(0)
	v_add_f32_e32 v0, v0, v114
	v_mov_b32_e32 v114, v0
	s_nop 1
	v_permlane32_swap_b32_e32 v0, v114
	s_and_saveexec_b64 s[12:13], s[36:37]
	s_cbranch_execz .LBB0_1120
	v_add_f32_e32 v0, v0, v114
	global_atomic_add_f32 v[154:155], v0, off offset:128
.LBB0_1120:
	s_or_b64 exec, exec, s[12:13]
	s_mov_b64 s[12:13], 0x18000
	v_or_b32_e32 v0, 48, v192
	v_lshl_add_u64 v[114:115], v[194:195], 0, s[12:13]
	s_mov_b64 s[12:13], 0x1a000
	s_waitcnt vmcnt(9)
	v_pk_fma_f32 v[112:113], v[112:113], v[80:81], v[136:137]
	v_pk_fma_f32 v[110:111], v[110:111], v[78:79], v[134:135]
	s_waitcnt vmcnt(8)
	v_pk_fma_f32 v[106:107], v[106:107], v[74:75], v[142:143]
	v_lshrrev_b32_e32 v0, 3, v0
	v_lshl_add_u64 v[116:117], v[194:195], 0, s[12:13]
	v_pk_fma_f32 v[108:109], v[108:109], v[76:77], v[144:145]
	global_store_dwordx4 v[114:115], v[110:113], off
	global_store_dwordx4 v[116:117], v[106:109], off
	v_and_or_b32 v0, v0, 14, s14
	v_pk_mul_f32 v[114:115], v[70:71], v[110:111]
	v_pk_mul_f32 v[124:125], v[66:67], v[106:107]
	v_mul_f32_e32 v111, v111, v111
	v_mul_f32_e32 v107, v107, v107
	v_lshlrev_b32_e32 v0, 10, v0
	v_fmac_f32_e32 v111, v110, v110
	v_mul_f32_e32 v110, v113, v113
	v_fmac_f32_e32 v107, v106, v106
	v_mul_f32_e32 v106, v109, v109
	s_mov_b64 s[12:13], 0x1c000
	v_bitop3_b32 v0, v122, v0, v123 bitop3:0xde
	v_pk_mul_f32 v[116:117], v[72:73], v[112:113]
	v_pk_mul_f32 v[122:123], v[68:69], v[108:109]
	v_fmac_f32_e32 v110, v112, v112
	v_fmac_f32_e32 v106, v108, v108
	v_lshl_add_u64 v[118:119], v[194:195], 0, s[12:13]
	s_mov_b64 s[12:13], 0x1e000
	v_cvt_pk_bf16_f32 v114, v114, v115
	v_cvt_pk_bf16_f32 v115, v116, v117
	v_cvt_pk_bf16_f32 v116, v124, v125
	v_cvt_pk_bf16_f32 v117, v122, v123
	v_lshl_add_u64 v[122:123], v[196:197], 0, v[0:1]
	v_add_f32_e32 v110, v111, v110
	v_add_f32_e32 v106, v107, v106
	s_waitcnt vmcnt(9)
	v_pk_fma_f32 v[104:105], v[104:105], v[56:57], v[132:133]
	v_pk_fma_f32 v[102:103], v[102:103], v[54:55], v[130:131]
	s_waitcnt vmcnt(8)
	v_pk_fma_f32 v[98:99], v[98:99], v[50:51], v[138:139]
	v_lshl_add_u64 v[120:121], v[194:195], 0, s[12:13]
	global_store_dwordx4 v[122:123], v[114:117], off
	v_pk_fma_f32 v[100:101], v[100:101], v[52:53], v[140:141]
	global_store_dwordx4 v[118:119], v[102:105], off
	global_store_dwordx4 v[120:121], v[98:101], off
	v_add_f32_e32 v114, v110, v106
	v_pk_mul_f32 v[106:107], v[46:47], v[102:103]
	v_pk_mul_f32 v[112:113], v[42:43], v[98:99]
	v_mul_f32_e32 v103, v103, v103
	v_mul_f32_e32 v99, v99, v99
	v_fmac_f32_e32 v103, v102, v102
	v_mul_f32_e32 v102, v105, v105
	v_fmac_f32_e32 v99, v98, v98
	v_mul_f32_e32 v98, v101, v101
	v_fmac_f32_e32 v102, v104, v104
	v_fmac_f32_e32 v98, v100, v100
	v_add_f32_e32 v102, v103, v102
	v_add_f32_e32 v98, v99, v98
	v_add_f32_e32 v98, v102, v98
	v_pk_mul_f32 v[110:111], v[44:45], v[100:101]
	v_add_f32_e32 v100, v114, v98
	ds_swizzle_b32 v101, v100 offset:swizzle(SWAP,16)
	v_pk_mul_f32 v[108:109], v[48:49], v[104:105]
	v_cvt_pk_bf16_f32 v106, v106, v107
	v_cvt_pk_bf16_f32 v107, v108, v109
	v_cvt_pk_bf16_f32 v108, v112, v113
	v_cvt_pk_bf16_f32 v109, v110, v111
	v_lshl_add_u64 v[98:99], v[156:157], 0, v[0:1]
	s_waitcnt lgkmcnt(0)
	v_add_f32_e32 v0, v100, v101
	global_store_dwordx4 v[98:99], v[106:109], off
	v_mov_b32_e32 v98, v0
	s_nop 1
	v_permlane32_swap_b32_e32 v0, v98
	s_and_saveexec_b64 s[12:13], s[36:37]
	s_cbranch_execz .LBB0_1122
	v_add_f32_e32 v0, v0, v98
	global_atomic_add_f32 v[154:155], v0, off offset:192
.LBB0_1122:
	s_or_b64 exec, exec, s[12:13]
	v_add_co_u32_e32 v134, vcc, 0x20000, v194
	s_nop 1
	v_addc_co_u32_e32 v135, vcc, 0, v195, vcc
	global_load_dwordx4 v[126:129], v[134:135], off
	v_add_co_u32_e32 v136, vcc, 0x22000, v194
	s_nop 1
	v_addc_co_u32_e32 v137, vcc, 0, v195, vcc
	global_load_dwordx4 v[130:133], v[136:137], off
	v_add_co_u32_e32 v122, vcc, 0x24000, v194
	s_nop 1
	v_addc_co_u32_e32 v123, vcc, 0, v195, vcc
	v_add_co_u32_e32 v124, vcc, 0x26000, v194
	global_load_dwordx4 v[114:117], v[122:123], off
	s_nop 0
	v_addc_co_u32_e32 v125, vcc, 0, v195, vcc
	global_load_dwordx4 v[118:121], v[124:125], off
	v_add_co_u32_e32 v98, vcc, 0x28000, v194
	s_nop 1
	v_addc_co_u32_e32 v99, vcc, 0, v195, vcc
	global_load_dwordx4 v[110:113], v[98:99], off
	v_add_co_u32_e32 v98, vcc, 0x2a000, v194
	s_waitcnt vmcnt(2)
	v_pk_fma_f32 v[88:89], v[88:89], v[56:57], v[116:117]
	v_addc_co_u32_e32 v99, vcc, 0, v195, vcc
	global_load_dwordx4 v[106:109], v[98:99], off
	v_add_co_u32_e32 v98, vcc, 0x2c000, v194
	v_pk_fma_f32 v[86:87], v[86:87], v[54:55], v[114:115]
	s_nop 0
	v_addc_co_u32_e32 v99, vcc, 0, v195, vcc
	global_load_dwordx4 v[102:105], v[98:99], off
	v_add_co_u32_e32 v98, vcc, 0x2e000, v194
	v_pk_fma_f32 v[96:97], v[96:97], v[80:81], v[128:129]
	s_nop 0
	v_addc_co_u32_e32 v99, vcc, 0, v195, vcc
	global_load_dwordx4 v[98:101], v[98:99], off
	v_add_u32_e32 v128, 0x80, v192
	v_pk_fma_f32 v[94:95], v[94:95], v[78:79], v[126:127]
	v_lshlrev_b32_e32 v0, 6, v128
	v_lshlrev_b32_e32 v126, 2, v128
	v_and_or_b32 v0, v0, s82, v206
	v_and_b32_e32 v126, 32, v126
	v_pk_fma_f32 v[92:93], v[92:93], v[76:77], v[132:133]
	v_bitop3_b32 v0, v0, s17, v126 bitop3:0xde
	v_lshlrev_b32_e32 v126, 7, v128
	v_ashrrev_i32_e32 v128, 3, v128
	v_pk_fma_f32 v[90:91], v[90:91], v[74:75], v[130:131]
	global_store_dwordx4 v[134:135], v[94:97], off
	global_store_dwordx4 v[136:137], v[90:93], off
	v_and_b32_e32 v136, 0xffffffe0, v128
	v_pk_mul_f32 v[130:131], v[72:73], v[96:97]
	v_pk_mul_f32 v[128:129], v[70:71], v[94:95]
	v_pk_mul_f32 v[132:133], v[68:69], v[92:93]
	v_cvt_pk_bf16_f32 v128, v128, v129
	v_cvt_pk_bf16_f32 v129, v130, v131
	v_cvt_pk_bf16_f32 v131, v132, v133
	v_add_u32_e32 v132, s15, v136
	v_ashrrev_i32_e32 v133, 31, v132
	v_pk_mul_f32 v[134:135], v[66:67], v[90:91]
	v_lshlrev_b64 v[132:133], 15, v[132:133]
	v_mul_f32_e32 v95, v95, v95
	v_mul_f32_e32 v91, v91, v91
	v_and_b32_e32 v126, 0x4000, v126
	v_mov_b32_e32 v127, v1
	v_lshl_add_u64 v[132:133], s[4:5], 0, v[132:133]
	v_fmac_f32_e32 v95, v94, v94
	v_mul_f32_e32 v94, v97, v97
	v_fmac_f32_e32 v91, v90, v90
	v_mul_f32_e32 v90, v93, v93
	v_lshl_add_u64 v[132:133], v[132:133], 0, v[126:127]
	v_fmac_f32_e32 v94, v96, v96
	v_fmac_f32_e32 v90, v92, v92
	v_cvt_pk_bf16_f32 v130, v134, v135
	v_lshl_add_u64 v[132:133], v[132:133], 0, v[0:1]
	v_add_f32_e32 v94, v95, v94
	v_add_f32_e32 v90, v91, v90
	s_waitcnt vmcnt(6)
	v_pk_fma_f32 v[84:85], v[84:85], v[52:53], v[120:121]
	global_store_dwordx4 v[132:133], v[128:131], off
	v_pk_mul_f32 v[92:93], v[48:49], v[88:89]
	v_pk_fma_f32 v[82:83], v[82:83], v[50:51], v[118:119]
	v_add_f32_e32 v128, v94, v90
	v_pk_mul_f32 v[90:91], v[46:47], v[86:87]
	v_pk_mul_f32 v[94:95], v[44:45], v[84:85]
	v_cvt_pk_bf16_f32 v90, v90, v91
	v_cvt_pk_bf16_f32 v91, v92, v93
	v_cvt_pk_bf16_f32 v93, v94, v95
	v_add_u32_e32 v94, s16, v136
	v_ashrrev_i32_e32 v95, 31, v94
	v_lshlrev_b64 v[94:95], 15, v[94:95]
	v_lshl_add_u64 v[94:95], s[4:5], 0, v[94:95]
	v_lshl_add_u64 v[94:95], v[94:95], 0, v[126:127]
	global_store_dwordx4 v[122:123], v[86:89], off
	global_store_dwordx4 v[124:125], v[82:85], off
	v_pk_mul_f32 v[96:97], v[42:43], v[82:83]
	v_lshl_add_u64 v[94:95], v[94:95], 0, v[0:1]
	v_mul_f32_e32 v0, v87, v87
	v_mul_f32_e32 v83, v83, v83
	v_fmac_f32_e32 v0, v86, v86
	v_mul_f32_e32 v86, v89, v89
	v_fmac_f32_e32 v83, v82, v82
	v_mul_f32_e32 v82, v85, v85
	v_fmac_f32_e32 v86, v88, v88
	v_fmac_f32_e32 v82, v84, v84
	v_add_f32_e32 v0, v0, v86
	v_add_f32_e32 v82, v83, v82
	v_add_f32_e32 v0, v0, v82
	v_add_f32_e32 v0, v128, v0
	ds_swizzle_b32 v82, v0 offset:swizzle(SWAP,16)
	v_cvt_pk_bf16_f32 v92, v96, v97
	global_store_dwordx4 v[94:95], v[90:93], off
	s_waitcnt lgkmcnt(0)
	v_add_f32_e32 v0, v0, v82
	v_mov_b32_e32 v82, v0
	s_nop 1
	v_permlane32_swap_b32_e32 v0, v82
	s_and_saveexec_b64 s[12:13], s[36:37]
	s_cbranch_execz .LBB0_1124
	v_add_f32_e32 v0, v0, v82
	global_atomic_add_f32 v[154:155], v0, off offset:512
.LBB0_1124:
	s_or_b64 exec, exec, s[12:13]
	s_mov_b64 s[12:13], 0x28000
	v_lshl_add_u64 v[82:83], v[194:195], 0, s[12:13]
	s_mov_b64 s[12:13], 0x2a000
	v_add_u32_e32 v92, 0x90, v192
	s_waitcnt vmcnt(9)
	v_pk_fma_f32 v[64:65], v[64:65], v[80:81], v[112:113]
	v_pk_fma_f32 v[62:63], v[62:63], v[78:79], v[110:111]
	v_lshl_add_u64 v[84:85], v[194:195], 0, s[12:13]
	s_waitcnt vmcnt(8)
	v_pk_fma_f32 v[60:61], v[60:61], v[76:77], v[108:109]
	v_pk_fma_f32 v[58:59], v[58:59], v[74:75], v[106:107]
	global_store_dwordx4 v[82:83], v[62:65], off
	global_store_dwordx4 v[84:85], v[58:61], off
	v_lshrrev_b32_e32 v83, 3, v92
	v_lshlrev_b32_e32 v0, 6, v92
	v_lshlrev_b32_e32 v82, 2, v92
	v_and_or_b32 v83, v83, 10, s14
	v_and_or_b32 v0, v0, s82, v206
	v_and_b32_e32 v82, 32, v82
	v_lshlrev_b32_e32 v83, 10, v83
	v_bitop3_b32 v0, v0, v83, v82 bitop3:0xde
	v_lshlrev_b32_e32 v82, 7, v92
	v_and_b32_e32 v90, 0x4000, v82
	v_ashrrev_i32_e32 v82, 3, v92
	v_and_b32_e32 v96, 0xffffffe0, v82
	v_pk_mul_f32 v[84:85], v[72:73], v[64:65]
	v_pk_mul_f32 v[82:83], v[70:71], v[62:63]
	v_pk_mul_f32 v[92:93], v[68:69], v[60:61]
	v_cvt_pk_bf16_f32 v82, v82, v83
	v_cvt_pk_bf16_f32 v83, v84, v85
	v_cvt_pk_bf16_f32 v85, v92, v93
	v_add_u32_e32 v92, s15, v96
	v_ashrrev_i32_e32 v93, 31, v92
	v_pk_mul_f32 v[94:95], v[66:67], v[58:59]
	v_lshlrev_b64 v[92:93], 15, v[92:93]
	v_mul_f32_e32 v63, v63, v63
	v_mul_f32_e32 v59, v59, v59
	v_mov_b32_e32 v91, v1
	v_lshl_add_u64 v[92:93], s[4:5], 0, v[92:93]
	v_fmac_f32_e32 v63, v62, v62
	v_mul_f32_e32 v62, v65, v65
	v_fmac_f32_e32 v59, v58, v58
	v_mul_f32_e32 v58, v61, v61
	s_mov_b64 s[12:13], 0x2c000
	v_lshl_add_u64 v[92:93], v[92:93], 0, v[90:91]
	v_fmac_f32_e32 v62, v64, v64
	v_fmac_f32_e32 v58, v60, v60
	v_lshl_add_u64 v[86:87], v[194:195], 0, s[12:13]
	s_mov_b64 s[12:13], 0x2e000
	v_cvt_pk_bf16_f32 v84, v94, v95
	v_lshl_add_u64 v[92:93], v[92:93], 0, v[0:1]
	v_add_f32_e32 v62, v63, v62
	v_add_f32_e32 v58, v59, v58
	s_waitcnt vmcnt(9)
	v_pk_fma_f32 v[40:41], v[40:41], v[56:57], v[104:105]
	v_pk_fma_f32 v[38:39], v[38:39], v[54:55], v[102:103]
	s_waitcnt vmcnt(8)
	v_pk_fma_f32 v[34:35], v[34:35], v[50:51], v[98:99]
	v_lshl_add_u64 v[88:89], v[194:195], 0, s[12:13]
	global_store_dwordx4 v[92:93], v[82:85], off
	v_pk_fma_f32 v[36:37], v[36:37], v[52:53], v[100:101]
	global_store_dwordx4 v[86:87], v[38:41], off
	global_store_dwordx4 v[88:89], v[34:37], off
	v_add_f32_e32 v82, v62, v58
	v_pk_mul_f32 v[58:59], v[46:47], v[38:39]
	v_pk_mul_f32 v[64:65], v[42:43], v[34:35]
	v_mul_f32_e32 v39, v39, v39
	v_mul_f32_e32 v35, v35, v35
	v_fmac_f32_e32 v39, v38, v38
	v_mul_f32_e32 v38, v41, v41
	v_fmac_f32_e32 v35, v34, v34
	v_mul_f32_e32 v34, v37, v37
	v_fmac_f32_e32 v38, v40, v40
	v_fmac_f32_e32 v34, v36, v36
	v_add_f32_e32 v38, v39, v38
	v_add_f32_e32 v34, v35, v34
	v_add_f32_e32 v34, v38, v34
	v_pk_mul_f32 v[60:61], v[48:49], v[40:41]
	v_pk_mul_f32 v[62:63], v[44:45], v[36:37]
	v_add_f32_e32 v36, v82, v34
	v_cvt_pk_bf16_f32 v58, v58, v59
	v_cvt_pk_bf16_f32 v59, v60, v61
	v_cvt_pk_bf16_f32 v61, v62, v63
	v_add_u32_e32 v62, s16, v96
	ds_swizzle_b32 v37, v36 offset:swizzle(SWAP,16)
	v_ashrrev_i32_e32 v63, 31, v62
	v_lshlrev_b64 v[62:63], 15, v[62:63]
	v_lshl_add_u64 v[34:35], s[4:5], 0, v[62:63]
	v_lshl_add_u64 v[34:35], v[34:35], 0, v[90:91]
	v_cvt_pk_bf16_f32 v60, v64, v65
	v_lshl_add_u64 v[34:35], v[34:35], 0, v[0:1]
	s_waitcnt lgkmcnt(0)
	v_add_f32_e32 v0, v36, v37
	global_store_dwordx4 v[34:35], v[58:61], off
	v_mov_b32_e32 v34, v0
	s_nop 1
	v_permlane32_swap_b32_e32 v0, v34
	s_and_saveexec_b64 s[12:13], s[36:37]
	s_cbranch_execz .LBB0_1126
	v_add_f32_e32 v0, v0, v34
	global_atomic_add_f32 v[154:155], v0, off offset:576
.LBB0_1126:
	s_or_b64 exec, exec, s[12:13]
	v_add_co_u32_e32 v102, vcc, 0x30000, v194
	s_nop 1
	v_addc_co_u32_e32 v103, vcc, 0, v195, vcc
	global_load_dwordx4 v[94:97], v[102:103], off
	v_add_co_u32_e32 v104, vcc, 0x32000, v194
	s_nop 1
	v_addc_co_u32_e32 v105, vcc, 0, v195, vcc
	global_load_dwordx4 v[98:101], v[104:105], off
	v_add_co_u32_e32 v90, vcc, 0x34000, v194
	s_nop 1
	v_addc_co_u32_e32 v91, vcc, 0, v195, vcc
	v_add_co_u32_e32 v92, vcc, 0x36000, v194
	global_load_dwordx4 v[82:85], v[90:91], off
	s_nop 0
	v_addc_co_u32_e32 v93, vcc, 0, v195, vcc
	global_load_dwordx4 v[86:89], v[92:93], off
	v_add_co_u32_e32 v34, vcc, 0x38000, v194
	s_nop 1
	v_addc_co_u32_e32 v35, vcc, 0, v195, vcc
	global_load_dwordx4 v[62:65], v[34:35], off
	v_add_co_u32_e32 v34, vcc, 0x3a000, v194
	s_waitcnt vmcnt(2)
	v_pk_fma_f32 v[24:25], v[24:25], v[56:57], v[84:85]
	v_addc_co_u32_e32 v35, vcc, 0, v195, vcc
	global_load_dwordx4 v[58:61], v[34:35], off
	v_add_co_u32_e32 v34, vcc, 0x3c000, v194
	v_pk_fma_f32 v[22:23], v[22:23], v[54:55], v[82:83]
	s_nop 0
	v_addc_co_u32_e32 v35, vcc, 0, v195, vcc
	global_load_dwordx4 v[38:41], v[34:35], off
	v_add_co_u32_e32 v34, vcc, 0x3e000, v194
	v_pk_fma_f32 v[32:33], v[32:33], v[80:81], v[96:97]
	s_nop 0
	v_addc_co_u32_e32 v35, vcc, 0, v195, vcc
	global_load_dwordx4 v[34:37], v[34:35], off
	v_add_u32_e32 v96, 0xa0, v192
	v_pk_fma_f32 v[30:31], v[30:31], v[78:79], v[94:95]
	v_lshrrev_b32_e32 v95, 3, v96
	v_lshlrev_b32_e32 v0, 6, v96
	v_lshlrev_b32_e32 v94, 2, v96
	v_and_or_b32 v95, v95, 12, s14
	v_and_or_b32 v0, v0, s82, v206
	v_and_b32_e32 v94, 32, v94
	v_lshlrev_b32_e32 v95, 10, v95
	v_pk_fma_f32 v[28:29], v[28:29], v[76:77], v[100:101]
	v_bitop3_b32 v0, v0, v95, v94 bitop3:0xde
	v_lshlrev_b32_e32 v94, 7, v96
	v_ashrrev_i32_e32 v96, 3, v96
	v_pk_fma_f32 v[26:27], v[26:27], v[74:75], v[98:99]
	global_store_dwordx4 v[102:103], v[30:33], off
	global_store_dwordx4 v[104:105], v[26:29], off
	v_and_b32_e32 v104, 0xffffffe0, v96
	v_pk_mul_f32 v[98:99], v[72:73], v[32:33]
	v_pk_mul_f32 v[96:97], v[70:71], v[30:31]
	v_pk_mul_f32 v[100:101], v[68:69], v[28:29]
	v_cvt_pk_bf16_f32 v96, v96, v97
	v_cvt_pk_bf16_f32 v97, v98, v99
	v_cvt_pk_bf16_f32 v99, v100, v101
	v_add_u32_e32 v100, s15, v104
	v_ashrrev_i32_e32 v101, 31, v100
	v_pk_mul_f32 v[102:103], v[66:67], v[26:27]
	v_lshlrev_b64 v[100:101], 15, v[100:101]
	v_mul_f32_e32 v31, v31, v31
	v_mul_f32_e32 v27, v27, v27
	v_and_b32_e32 v94, 0x4000, v94
	v_mov_b32_e32 v95, v1
	v_lshl_add_u64 v[100:101], s[4:5], 0, v[100:101]
	v_fmac_f32_e32 v31, v30, v30
	v_mul_f32_e32 v30, v33, v33
	v_fmac_f32_e32 v27, v26, v26
	v_mul_f32_e32 v26, v29, v29
	v_lshl_add_u64 v[100:101], v[100:101], 0, v[94:95]
	v_fmac_f32_e32 v30, v32, v32
	v_fmac_f32_e32 v26, v28, v28
	v_cvt_pk_bf16_f32 v98, v102, v103
	v_lshl_add_u64 v[100:101], v[100:101], 0, v[0:1]
	v_add_f32_e32 v30, v31, v30
	v_add_f32_e32 v26, v27, v26
	s_waitcnt vmcnt(6)
	v_pk_fma_f32 v[20:21], v[20:21], v[52:53], v[88:89]
	global_store_dwordx4 v[100:101], v[96:99], off
	v_pk_mul_f32 v[28:29], v[48:49], v[24:25]
	v_pk_fma_f32 v[18:19], v[18:19], v[50:51], v[86:87]
	v_add_f32_e32 v96, v30, v26
	v_pk_mul_f32 v[26:27], v[46:47], v[22:23]
	v_pk_mul_f32 v[30:31], v[44:45], v[20:21]
	v_cvt_pk_bf16_f32 v26, v26, v27
	v_cvt_pk_bf16_f32 v27, v28, v29
	v_cvt_pk_bf16_f32 v29, v30, v31
	v_add_u32_e32 v30, s16, v104
	v_ashrrev_i32_e32 v31, 31, v30
	v_lshlrev_b64 v[30:31], 15, v[30:31]
	v_lshl_add_u64 v[30:31], s[4:5], 0, v[30:31]
	v_lshl_add_u64 v[30:31], v[30:31], 0, v[94:95]
	global_store_dwordx4 v[90:91], v[22:25], off
	global_store_dwordx4 v[92:93], v[18:21], off
	v_pk_mul_f32 v[32:33], v[42:43], v[18:19]
	v_lshl_add_u64 v[30:31], v[30:31], 0, v[0:1]
	v_mul_f32_e32 v0, v23, v23
	v_mul_f32_e32 v19, v19, v19
	v_fmac_f32_e32 v0, v22, v22
	v_mul_f32_e32 v22, v25, v25
	v_fmac_f32_e32 v19, v18, v18
	v_mul_f32_e32 v18, v21, v21
	v_fmac_f32_e32 v22, v24, v24
	v_fmac_f32_e32 v18, v20, v20
	v_add_f32_e32 v0, v0, v22
	v_add_f32_e32 v18, v19, v18
	v_add_f32_e32 v0, v0, v18
	v_add_f32_e32 v0, v96, v0
	ds_swizzle_b32 v18, v0 offset:swizzle(SWAP,16)
	v_cvt_pk_bf16_f32 v28, v32, v33
	global_store_dwordx4 v[30:31], v[26:29], off
	s_waitcnt lgkmcnt(0)
	v_add_f32_e32 v0, v0, v18
	v_mov_b32_e32 v18, v0
	s_nop 1
	v_permlane32_swap_b32_e32 v0, v18
	s_and_saveexec_b64 s[12:13], s[36:37]
	s_cbranch_execz .LBB0_1128
	v_add_f32_e32 v0, v0, v18
	global_atomic_add_f32 v[154:155], v0, off offset:640
.LBB0_1128:
	s_or_b64 exec, exec, s[12:13]
	s_mov_b64 s[12:13], 0x38000
	v_lshl_add_u64 v[18:19], v[194:195], 0, s[12:13]
	s_mov_b64 s[12:13], 0x3a000
	v_add_u32_e32 v28, 0xb0, v192
	s_waitcnt vmcnt(9)
	v_pk_fma_f32 v[16:17], v[16:17], v[80:81], v[64:65]
	v_pk_fma_f32 v[14:15], v[14:15], v[78:79], v[62:63]
	v_lshl_add_u64 v[20:21], v[194:195], 0, s[12:13]
	s_waitcnt vmcnt(8)
	v_pk_fma_f32 v[12:13], v[12:13], v[76:77], v[60:61]
	v_pk_fma_f32 v[10:11], v[10:11], v[74:75], v[58:59]
	global_store_dwordx4 v[18:19], v[14:17], off
	global_store_dwordx4 v[20:21], v[10:13], off
	v_lshrrev_b32_e32 v19, 3, v28
	v_lshlrev_b32_e32 v0, 6, v28
	v_lshlrev_b32_e32 v18, 2, v28
	v_and_or_b32 v19, v19, 14, s14
	v_and_or_b32 v0, v0, s82, v206
	v_and_b32_e32 v18, 32, v18
	v_lshlrev_b32_e32 v19, 10, v19
	v_bitop3_b32 v0, v0, v19, v18 bitop3:0xde
	v_lshlrev_b32_e32 v18, 7, v28
	v_and_b32_e32 v26, 0x4000, v18
	v_ashrrev_i32_e32 v18, 3, v28
	v_and_b32_e32 v32, 0xffffffe0, v18
	v_pk_mul_f32 v[20:21], v[72:73], v[16:17]
	v_pk_mul_f32 v[18:19], v[70:71], v[14:15]
	v_pk_mul_f32 v[28:29], v[68:69], v[12:13]
	v_cvt_pk_bf16_f32 v18, v18, v19
	v_cvt_pk_bf16_f32 v19, v20, v21
	v_cvt_pk_bf16_f32 v21, v28, v29
	v_add_u32_e32 v28, s15, v32
	v_ashrrev_i32_e32 v29, 31, v28
	v_pk_mul_f32 v[30:31], v[66:67], v[10:11]
	v_lshlrev_b64 v[28:29], 15, v[28:29]
	v_mul_f32_e32 v15, v15, v15
	v_mul_f32_e32 v11, v11, v11
	v_mov_b32_e32 v27, v1
	v_lshl_add_u64 v[28:29], s[4:5], 0, v[28:29]
	v_fmac_f32_e32 v15, v14, v14
	v_mul_f32_e32 v14, v17, v17
	v_fmac_f32_e32 v11, v10, v10
	v_mul_f32_e32 v10, v13, v13
	s_mov_b64 s[12:13], 0x3c000
	v_lshl_add_u64 v[28:29], v[28:29], 0, v[26:27]
	v_fmac_f32_e32 v14, v16, v16
	v_fmac_f32_e32 v10, v12, v12
	v_lshl_add_u64 v[22:23], v[194:195], 0, s[12:13]
	s_mov_b64 s[12:13], 0x3e000
	v_cvt_pk_bf16_f32 v20, v30, v31
	v_lshl_add_u64 v[28:29], v[28:29], 0, v[0:1]
	v_add_f32_e32 v14, v15, v14
	v_add_f32_e32 v10, v11, v10
	s_waitcnt vmcnt(9)
	v_pk_fma_f32 v[8:9], v[8:9], v[56:57], v[40:41]
	v_pk_fma_f32 v[6:7], v[6:7], v[54:55], v[38:39]
	s_waitcnt vmcnt(8)
	v_pk_fma_f32 v[2:3], v[2:3], v[50:51], v[34:35]
	v_lshl_add_u64 v[24:25], v[194:195], 0, s[12:13]
	global_store_dwordx4 v[28:29], v[18:21], off
	v_pk_fma_f32 v[4:5], v[4:5], v[52:53], v[36:37]
	global_store_dwordx4 v[22:23], v[6:9], off
	global_store_dwordx4 v[24:25], v[2:5], off
	v_add_f32_e32 v18, v14, v10
	v_pk_mul_f32 v[10:11], v[46:47], v[6:7]
	v_pk_mul_f32 v[16:17], v[42:43], v[2:3]
	v_mul_f32_e32 v7, v7, v7
	v_mul_f32_e32 v3, v3, v3
	v_fmac_f32_e32 v7, v6, v6
	v_mul_f32_e32 v6, v9, v9
	v_fmac_f32_e32 v3, v2, v2
	v_mul_f32_e32 v2, v5, v5
	v_fmac_f32_e32 v6, v8, v8
	v_fmac_f32_e32 v2, v4, v4
	v_add_f32_e32 v6, v7, v6
	v_add_f32_e32 v2, v3, v2
	v_add_f32_e32 v2, v6, v2
	v_pk_mul_f32 v[12:13], v[48:49], v[8:9]
	v_pk_mul_f32 v[14:15], v[44:45], v[4:5]
	v_add_f32_e32 v4, v18, v2
	v_cvt_pk_bf16_f32 v10, v10, v11
	v_cvt_pk_bf16_f32 v11, v12, v13
	v_cvt_pk_bf16_f32 v13, v14, v15
	v_add_u32_e32 v14, s16, v32
	ds_swizzle_b32 v5, v4 offset:swizzle(SWAP,16)
	v_ashrrev_i32_e32 v15, 31, v14
	v_lshlrev_b64 v[14:15], 15, v[14:15]
	v_lshl_add_u64 v[2:3], s[4:5], 0, v[14:15]
	v_lshl_add_u64 v[2:3], v[2:3], 0, v[26:27]
	v_cvt_pk_bf16_f32 v12, v16, v17
	v_lshl_add_u64 v[2:3], v[2:3], 0, v[0:1]
	s_waitcnt lgkmcnt(0)
	v_add_f32_e32 v0, v4, v5
	global_store_dwordx4 v[2:3], v[10:13], off
	v_mov_b32_e32 v2, v0
	s_nop 1
	v_permlane32_swap_b32_e32 v0, v2
	s_and_saveexec_b64 s[12:13], s[36:37]
	s_cbranch_execz .LBB0_1130
	v_add_f32_e32 v0, v0, v2
	global_atomic_add_f32 v[154:155], v0, off offset:704

.LBB0_1134:
	v_readlane_b32 s2, v255, 23
	v_readlane_b32 s4, v253, 5
	s_add_i32 s26, s2, 5
	v_readlane_b32 s5, v253, 6
	s_cmp_ge_i32 s26, s5
	v_readlane_b32 s6, v253, 7
	v_readlane_b32 s7, v253, 8
	s_cbranch_scc1 .LBB0_285
	s_cmp_lt_u32 s23, 3
	s_cbranch_scc1 .LBB0_285
	s_waitcnt vmcnt(0)
	s_waitcnt vmcnt(0)
	s_barrier
	v_mbcnt_lo_u32_b32 v0, -1, 0
	v_mbcnt_hi_u32_b32 v0, -1, v0
	s_nop 0
	v_or_b32_e32 v0, s81, v0
	v_cmp_eq_u32_e32 vcc, 0, v0
	s_and_saveexec_b64 s[2:3], vcc
	s_cbranch_execz .LBB0_284
	v_readlane_b32 s4, v254, 55
	s_waitcnt vmcnt(0) expcnt(0) lgkmcnt(0)
	s_nop 0
	v_mov_b32_e32 v0, s4
	ds_read_b32 v3, v0
	v_readlane_b32 s4, v254, 56
	s_waitcnt lgkmcnt(0)
	v_cmp_ne_u32_e32 vcc, 0, v3
	v_mov_b32_e32 v0, s4
	ds_read_b32 v2, v0
	s_cbranch_vccnz .LBB0_1151
	v_readlane_b32 s6, v253, 0
	v_readlane_b32 s7, v253, 1
	s_load_dwordx2 s[4:5], s[6:7], 0x4
	s_mov_b32 s15, 1
	s_waitcnt lgkmcnt(0)
	s_mul_i32 s14, s4, s21
	s_mul_i32 s14, s14, s5
	s_branch .LBB0_1139

.LBB0_1286:
	s_and_b64 s[4:5], s[4:5], exec
	s_cselect_b32 s4, s25, s7
	s_cselect_b32 s5, s24, s6
	v_mov_b32_e32 v147, s4
	s_lshl_b32 s4, s74, 3
	s_add_i32 s4, s4, s73
	v_add_u32_e32 v192, s12, v222
	v_mov_b32_e32 v146, s5
	s_ashr_i32 s5, s4, 31
	v_ashrrev_i32_e32 v193, 31, v192
	s_lshl_b64 s[4:5], s[4:5], 18
	v_lshl_add_u64 v[198:199], v[194:195], 2, v[146:147]
	v_lshlrev_b64 v[146:147], 13, v[192:193]
	v_lshl_add_u64 v[196:197], v[190:191], 0, s[4:5]
	v_lshl_add_u64 v[146:147], v[198:199], 0, v[146:147]
	v_cndmask_b32_e64 v149, v147, v197, s[38:39]
	v_cndmask_b32_e64 v148, v146, v196, s[38:39]
	s_mov_b64 s[4:5], 0x2000
	global_load_dwordx4 v[240:243], v[148:149], off
	v_lshl_add_u64 v[148:149], v[146:147], 0, 16
	v_lshl_add_u64 v[220:221], v[196:197], 0, s[4:5]
	v_cndmask_b32_e64 v149, v149, v221, s[38:39]
	v_cndmask_b32_e64 v148, v148, v220, s[38:39]
	s_mov_b64 s[12:13], 0x200
	s_mov_b64 s[74:75], 0x210
	s_mov_b64 s[4:5], 0x6000
	global_load_dwordx4 v[244:247], v[148:149], off
	v_lshl_add_u64 v[148:149], v[146:147], 0, s[12:13]
	v_lshl_add_u64 v[146:147], v[146:147], 0, s[74:75]
	v_lshl_add_u64 v[216:217], v[196:197], 0, s[4:5]
	v_or_b32_e32 v204, 16, v192
	v_cndmask_b32_e64 v147, v147, v217, s[38:39]
	v_cndmask_b32_e64 v146, v146, v216, s[38:39]
	v_ashrrev_i32_e32 v205, 31, v204
	v_lshl_add_u64 v[214:215], v[196:197], 0, s[8:9]
	global_load_dwordx4 v[174:177], v[146:147], off
	v_lshlrev_b64 v[146:147], 13, v[204:205]
	s_mov_b64 s[4:5], 0x8000
	v_cndmask_b32_e64 v149, v149, v215, s[38:39]
	v_cndmask_b32_e64 v148, v148, v214, s[38:39]
	v_lshl_add_u64 v[146:147], v[198:199], 0, v[146:147]
	v_lshl_add_u64 v[206:207], v[196:197], 0, s[4:5]
	global_load_dwordx4 v[178:181], v[148:149], off
	v_cndmask_b32_e64 v149, v147, v207, s[38:39]
	v_cndmask_b32_e64 v148, v146, v206, s[38:39]
	s_mov_b64 s[4:5], 0xa000
	global_load_dwordx4 v[158:161], v[148:149], off
	v_lshl_add_u64 v[148:149], v[146:147], 0, 16
	v_lshl_add_u64 v[212:213], v[196:197], 0, s[4:5]
	s_mov_b64 s[4:5], 0xc000
	v_cndmask_b32_e64 v149, v149, v213, s[38:39]
	v_cndmask_b32_e64 v148, v148, v212, s[38:39]
	v_lshl_add_u64 v[200:201], v[196:197], 0, s[4:5]
	s_mov_b64 s[4:5], 0xe000
	global_load_dwordx4 v[154:157], v[148:149], off
	v_lshl_add_u64 v[148:149], v[146:147], 0, s[12:13]
	v_lshl_add_u64 v[146:147], v[146:147], 0, s[74:75]
	v_lshl_add_u64 v[202:203], v[196:197], 0, s[4:5]
	v_cndmask_b32_e64 v149, v149, v201, s[38:39]
	v_cndmask_b32_e64 v148, v148, v200, s[38:39]
	v_cndmask_b32_e64 v147, v147, v203, s[38:39]
	v_cndmask_b32_e64 v146, v146, v202, s[38:39]
	global_load_dwordx4 v[150:153], v[148:149], off
	v_lshlrev_b64 v[218:219], 11, v[192:193]
	global_load_dwordx4 v[146:149], v[146:147], off
	s_waitcnt vmcnt(0)
	v_pk_mul_f32 v[184:185], v[184:185], 0.5 op_sel_hi:[1,0]
	v_pk_mul_f32 v[182:183], v[182:183], 0.5 op_sel_hi:[1,0]
	v_pk_mul_f32 v[172:173], v[172:173], 0.5 op_sel_hi:[1,0]
	v_pk_mul_f32 v[170:171], v[170:171], 0.5 op_sel_hi:[1,0]
	v_cndmask_b32_e64 v0, 0, 1, s[50:51]
	v_lshl_add_u64 v[218:219], v[218:219], 0, v[194:195]
	v_cmp_ne_u32_e64 s[4:5], 1, v0
	s_andn2_b64 vcc, exec, s[50:51]
	v_lshl_add_u64 v[218:219], v[218:219], 2, s[30:31]
	v_pk_fma_f32 v[144:145], v[144:145], v[172:173], v[242:243]
	v_pk_fma_f32 v[142:143], v[142:143], v[170:171], v[240:241]
	v_pk_fma_f32 v[140:141], v[140:141], v[184:185], v[246:247]
	v_pk_fma_f32 v[138:139], v[138:139], v[182:183], v[244:245]
	s_cbranch_vccnz .LBB0_1385
	global_store_dwordx4 v[218:219], v[142:145], off
	global_store_dwordx4 v[218:219], v[138:141], off offset:16
	s_cbranch_execnz .LBB0_1289
.LBB0_1288:
	global_store_dwordx4 v[196:197], v[142:145], off
	global_store_dwordx4 v[220:221], v[138:141], off
.LBB0_1289:
	v_lshlrev_b32_e32 v0, 1, v194
	v_bfe_u32 v220, v194, 5, 1
	v_and_b32_e32 v221, 48, v0
	v_ashrrev_i32_e32 v0, 3, v192
	v_and_b32_e32 v240, 0xffffffe0, v0
	v_or_b32_e32 v0, s70, v220
	v_lshlrev_b32_e32 v208, 6, v192
	v_lshlrev_b32_e32 v226, 10, v0
	v_lshlrev_b32_e32 v0, 2, v192
	v_and_or_b32 v208, v208, s82, v221
	v_and_b32_e32 v0, 32, v0
	v_bitop3_b32 v0, v208, v226, v0 bitop3:0xde
	s_and_b64 vcc, exec, s[2:3]
	v_mov_b32_e32 v241, 0
	s_cbranch_vccnz .LBB0_1291
	v_pk_mul_f32 v[234:235], v[72:73], v[144:145]
	s_ashr_i32 s12, s14, 6
	v_cvt_pk_bf16_f32 v243, v234, v235
	v_add_u32_e32 v234, s12, v240
	v_ashrrev_i32_e32 v235, 31, v234
	v_lshlrev_b64 v[234:235], 15, v[234:235]
	v_pk_mul_f32 v[236:237], v[70:71], v[142:143]
	v_pk_mul_f32 v[246:247], v[68:69], v[140:141]
	v_pk_mul_f32 v[244:245], v[66:67], v[138:139]
	v_lshl_add_u64 v[234:235], s[52:53], 0, v[234:235]
	v_cvt_pk_bf16_f32 v242, v236, v237
	v_cvt_pk_bf16_f32 v244, v244, v245
	v_cvt_pk_bf16_f32 v245, v246, v247
	v_lshl_add_u64 v[234:235], v[234:235], 0, v[0:1]
	global_store_dwordx4 v[234:235], v[242:245], off
	v_mov_b32_e32 v235, v138
	v_mov_b32_e32 v138, v143
	v_mov_b32_e32 v143, v140
	v_mov_b32_e32 v140, v145
	v_mov_b32_e32 v234, v142
	v_pk_mul_f32 v[138:139], v[138:139], v[138:139]
	v_mov_b32_e32 v142, v144
	v_pk_mul_f32 v[140:141], v[140:141], v[140:141]
	v_pk_fma_f32 v[138:139], v[234:235], v[234:235], v[138:139]
	v_pk_fma_f32 v[140:141], v[142:143], v[142:143], v[140:141]
	s_nop 0
	v_pk_add_f32 v[138:139], v[138:139], v[140:141]
	s_nop 0
	v_add_f32_e32 v241, v138, v139
.LBB0_1291:
	v_pk_mul_f32 v[140:141], v[168:169], 0.5 op_sel_hi:[1,0]
	v_pk_mul_f32 v[138:139], v[166:167], 0.5 op_sel_hi:[1,0]
	v_pk_mul_f32 v[142:143], v[164:165], 0.5 op_sel_hi:[1,0]
	v_pk_mul_f32 v[144:145], v[162:163], 0.5 op_sel_hi:[1,0]
	v_pk_fma_f32 v[136:137], v[136:137], v[142:143], v[180:181]
	v_pk_fma_f32 v[134:135], v[134:135], v[144:145], v[178:179]
	v_pk_fma_f32 v[132:133], v[132:133], v[140:141], v[176:177]
	s_and_b64 vcc, exec, s[4:5]
	v_pk_fma_f32 v[130:131], v[130:131], v[138:139], v[174:175]
	s_cbranch_vccnz .LBB0_1386
	global_store_dwordx4 v[218:219], v[134:137], off offset:512
	global_store_dwordx4 v[218:219], v[130:133], off offset:528
	s_cbranch_execnz .LBB0_1294
.LBB0_1293:
	global_store_dwordx4 v[214:215], v[134:137], off
	global_store_dwordx4 v[216:217], v[130:133], off
.LBB0_1294:
	s_and_b64 vcc, exec, s[2:3]
	s_cbranch_vccnz .LBB0_1298
	v_pk_mul_f32 v[162:163], v[62:63], v[134:135]
	v_pk_mul_f32 v[168:169], v[58:59], v[130:131]
	v_mul_f32_e32 v135, v135, v135
	v_mul_f32_e32 v131, v131, v131
	v_fmac_f32_e32 v135, v134, v134
	v_mul_f32_e32 v134, v137, v137
	v_fmac_f32_e32 v131, v130, v130
	v_mul_f32_e32 v130, v133, v133
	v_fmac_f32_e32 v134, v136, v136
	v_fmac_f32_e32 v130, v132, v132
	v_add_f32_e32 v134, v135, v134
	v_add_f32_e32 v130, v131, v130
	v_add_f32_e32 v130, v134, v130
	v_pk_mul_f32 v[166:167], v[60:61], v[132:133]
	v_add_f32_e32 v132, v130, v241
	v_pk_mul_f32 v[164:165], v[64:65], v[136:137]
	s_ashr_i32 s12, s14, 6
	ds_swizzle_b32 v133, v132 offset:swizzle(SWAP,16)
	v_cvt_pk_bf16_f32 v162, v162, v163
	v_cvt_pk_bf16_f32 v163, v164, v165
	v_cvt_pk_bf16_f32 v165, v166, v167
	v_add3_u32 v166, v240, s12, 2
	v_ashrrev_i32_e32 v167, 31, v166
	v_lshlrev_b64 v[130:131], 15, v[166:167]
	v_lshl_add_u64 v[130:131], s[52:53], 0, v[130:131]
	v_cvt_pk_bf16_f32 v164, v168, v169
	v_lshl_add_u64 v[130:131], v[130:131], 0, v[0:1]
	s_waitcnt lgkmcnt(0)
	v_add_f32_e32 v0, v132, v133
	global_store_dwordx4 v[130:131], v[162:165], off
	v_mov_b32_e32 v130, v0
	s_nop 1
	v_permlane32_swap_b32_e32 v0, v130
	s_and_saveexec_b64 s[12:13], s[36:37]
	s_cbranch_execz .LBB0_1297
	v_lshl_add_u64 v[132:133], v[192:193], 2, s[46:47]
	v_add_f32_e32 v0, v0, v130
	global_atomic_add_f32 v[132:133], v0, off

.LBB0_1298:
	v_lshlrev_b64 v[130:131], 11, v[204:205]
	v_lshl_add_u64 v[130:131], v[130:131], 0, v[194:195]
	v_pk_fma_f32 v[128:129], v[128:129], v[172:173], v[160:161]
	v_pk_fma_f32 v[126:127], v[126:127], v[170:171], v[158:159]
	v_pk_fma_f32 v[124:125], v[124:125], v[184:185], v[156:157]
	v_pk_fma_f32 v[122:123], v[122:123], v[182:183], v[154:155]
	s_and_b64 vcc, exec, s[4:5]
	v_lshl_add_u64 v[130:131], v[130:131], 2, s[30:31]
	s_cbranch_vccnz .LBB0_1387
	global_store_dwordx4 v[130:131], v[126:129], off
	global_store_dwordx4 v[130:131], v[122:125], off offset:16
	s_cbranch_execnz .LBB0_1301
.LBB0_1300:
	global_store_dwordx4 v[206:207], v[126:129], off
	global_store_dwordx4 v[212:213], v[122:125], off
.LBB0_1301:
	v_lshrrev_b32_e32 v0, 3, v204
	v_and_or_b32 v0, v0, 10, v220
	v_lshlrev_b32_e32 v132, 6, v204
	v_lshlrev_b32_e32 v133, 2, v204
	v_and_or_b32 v132, v132, s82, v221
	v_lshlrev_b32_e32 v0, 10, v0
	v_and_b32_e32 v133, 32, v133
	v_bitop3_b32 v0, v132, v0, v133 bitop3:0xde
	s_and_b64 vcc, exec, s[2:3]
	v_mov_b32_e32 v132, 0
	s_cbranch_vccnz .LBB0_1303
	v_pk_mul_f32 v[134:135], v[72:73], v[128:129]
	v_pk_mul_f32 v[132:133], v[70:71], v[126:127]
	v_pk_mul_f32 v[136:137], v[68:69], v[124:125]
	s_ashr_i32 s12, s14, 6
	v_cvt_pk_bf16_f32 v132, v132, v133
	v_cvt_pk_bf16_f32 v133, v134, v135
	v_cvt_pk_bf16_f32 v135, v136, v137
	v_add_u32_e32 v136, s12, v240
	v_ashrrev_i32_e32 v137, 31, v136
	v_lshlrev_b64 v[136:137], 15, v[136:137]
	v_pk_mul_f32 v[154:155], v[66:67], v[122:123]
	v_lshl_add_u64 v[136:137], s[52:53], 0, v[136:137]
	v_cvt_pk_bf16_f32 v134, v154, v155
	v_lshl_add_u64 v[136:137], v[136:137], 0, v[0:1]
	global_store_dwordx4 v[136:137], v[132:135], off
	s_nop 1
	v_mov_b32_e32 v133, v122
	v_mov_b32_e32 v122, v127
	v_mov_b32_e32 v127, v124
	v_mov_b32_e32 v124, v129
	v_mov_b32_e32 v132, v126
	v_pk_mul_f32 v[122:123], v[122:123], v[122:123]
	v_mov_b32_e32 v126, v128
	v_pk_mul_f32 v[124:125], v[124:125], v[124:125]
	v_pk_fma_f32 v[122:123], v[132:133], v[132:133], v[122:123]
	v_pk_fma_f32 v[124:125], v[126:127], v[126:127], v[124:125]
	s_nop 0
	v_pk_add_f32 v[122:123], v[122:123], v[124:125]
	s_nop 0
	v_add_f32_e32 v132, v122, v123
.LBB0_1303:
	v_pk_fma_f32 v[120:121], v[120:121], v[142:143], v[152:153]
	v_pk_fma_f32 v[118:119], v[118:119], v[144:145], v[150:151]
	v_pk_fma_f32 v[116:117], v[116:117], v[140:141], v[148:149]
	s_and_b64 vcc, exec, s[4:5]
	v_pk_fma_f32 v[114:115], v[114:115], v[138:139], v[146:147]
	s_cbranch_vccnz .LBB0_1388
	global_store_dwordx4 v[130:131], v[118:121], off offset:512
	global_store_dwordx4 v[130:131], v[114:117], off offset:528
	s_cbranch_execnz .LBB0_1306
.LBB0_1305:
	global_store_dwordx4 v[200:201], v[118:121], off
	global_store_dwordx4 v[202:203], v[114:117], off
.LBB0_1306:
	s_and_b64 vcc, exec, s[2:3]
	s_cbranch_vccnz .LBB0_1310
	v_pk_mul_f32 v[122:123], v[62:63], v[118:119]
	v_pk_mul_f32 v[128:129], v[58:59], v[114:115]
	v_mul_f32_e32 v119, v119, v119
	v_mul_f32_e32 v115, v115, v115
	v_fmac_f32_e32 v119, v118, v118
	v_mul_f32_e32 v118, v121, v121
	v_fmac_f32_e32 v115, v114, v114
	v_mul_f32_e32 v114, v117, v117
	v_fmac_f32_e32 v118, v120, v120
	v_fmac_f32_e32 v114, v116, v116
	v_add_f32_e32 v118, v119, v118
	v_add_f32_e32 v114, v115, v114
	v_add_f32_e32 v114, v118, v114
	v_pk_mul_f32 v[126:127], v[60:61], v[116:117]
	v_add_f32_e32 v116, v114, v132
	v_pk_mul_f32 v[124:125], v[64:65], v[120:121]
	s_ashr_i32 s12, s14, 6
	ds_swizzle_b32 v117, v116 offset:swizzle(SWAP,16)
	v_cvt_pk_bf16_f32 v122, v122, v123
	v_cvt_pk_bf16_f32 v123, v124, v125
	v_cvt_pk_bf16_f32 v125, v126, v127
	v_add3_u32 v126, v240, s12, 2
	v_ashrrev_i32_e32 v127, 31, v126
	v_lshlrev_b64 v[114:115], 15, v[126:127]
	v_lshl_add_u64 v[114:115], s[52:53], 0, v[114:115]
	v_cvt_pk_bf16_f32 v124, v128, v129
	v_lshl_add_u64 v[114:115], v[114:115], 0, v[0:1]
	s_waitcnt lgkmcnt(0)
	v_add_f32_e32 v0, v116, v117
	global_store_dwordx4 v[114:115], v[122:125], off
	v_mov_b32_e32 v114, v0
	s_nop 1
	v_permlane32_swap_b32_e32 v0, v114
	s_and_saveexec_b64 s[12:13], s[36:37]
	s_cbranch_execz .LBB0_1309
	v_lshl_add_u64 v[116:117], v[192:193], 2, s[46:47]
	v_add_f32_e32 v0, v0, v114
	global_atomic_add_f32 v[116:117], v0, off offset:64

.LBB0_1310:
	v_or_b32_e32 v160, 32, v192
	v_ashrrev_i32_e32 v161, 31, v160
	v_lshlrev_b64 v[114:115], 13, v[160:161]
	s_mov_b64 s[12:13], 0x10000
	v_lshl_add_u64 v[114:115], v[198:199], 0, v[114:115]
	v_lshl_add_u64 v[162:163], v[196:197], 0, s[12:13]
	v_cndmask_b32_e64 v117, v115, v163, s[38:39]
	v_cndmask_b32_e64 v116, v114, v162, s[38:39]
	s_mov_b64 s[12:13], 0x12000
	global_load_dwordx4 v[174:177], v[116:117], off
	v_lshl_add_u64 v[116:117], v[114:115], 0, 16
	v_lshl_add_u64 v[166:167], v[196:197], 0, s[12:13]
	s_mov_b64 s[12:13], 0x14000
	v_cndmask_b32_e64 v117, v117, v167, s[38:39]
	v_cndmask_b32_e64 v116, v116, v166, s[38:39]
	s_mov_b64 s[74:75], 0x200
	v_lshl_add_u64 v[156:157], v[196:197], 0, s[12:13]
	s_mov_b64 s[76:77], 0x210
	s_mov_b64 s[12:13], 0x16000
	global_load_dwordx4 v[178:181], v[116:117], off
	v_lshl_add_u64 v[116:117], v[114:115], 0, s[74:75]
	v_lshl_add_u64 v[114:115], v[114:115], 0, s[76:77]
	v_lshl_add_u64 v[158:159], v[196:197], 0, s[12:13]
	v_or_b32_e32 v150, 48, v192
	v_cndmask_b32_e64 v115, v115, v159, s[38:39]
	v_cndmask_b32_e64 v114, v114, v158, s[38:39]
	v_ashrrev_i32_e32 v151, 31, v150
	global_load_dwordx4 v[130:133], v[114:115], off
	v_lshlrev_b64 v[114:115], 13, v[150:151]
	s_mov_b64 s[12:13], 0x18000
	v_cndmask_b32_e64 v117, v117, v157, s[38:39]
	v_cndmask_b32_e64 v116, v116, v156, s[38:39]
	v_lshl_add_u64 v[114:115], v[198:199], 0, v[114:115]
	v_lshl_add_u64 v[152:153], v[196:197], 0, s[12:13]
	global_load_dwordx4 v[134:137], v[116:117], off
	v_cndmask_b32_e64 v117, v115, v153, s[38:39]
	v_cndmask_b32_e64 v116, v114, v152, s[38:39]
	s_mov_b64 s[12:13], 0x1a000
	global_load_dwordx4 v[126:129], v[116:117], off
	v_lshl_add_u64 v[116:117], v[114:115], 0, 16
	v_lshl_add_u64 v[154:155], v[196:197], 0, s[12:13]
	s_mov_b64 s[12:13], 0x1c000
	v_cndmask_b32_e64 v117, v117, v155, s[38:39]
	v_cndmask_b32_e64 v116, v116, v154, s[38:39]
	v_lshl_add_u64 v[146:147], v[196:197], 0, s[12:13]
	s_mov_b64 s[12:13], 0x1e000
	global_load_dwordx4 v[122:125], v[116:117], off
	v_lshl_add_u64 v[116:117], v[114:115], 0, s[74:75]
	v_lshl_add_u64 v[114:115], v[114:115], 0, s[76:77]
	v_lshl_add_u64 v[148:149], v[196:197], 0, s[12:13]
	v_cndmask_b32_e64 v117, v117, v147, s[38:39]
	v_cndmask_b32_e64 v116, v116, v146, s[38:39]
	v_cndmask_b32_e64 v115, v115, v149, s[38:39]
	v_cndmask_b32_e64 v114, v114, v148, s[38:39]
	global_load_dwordx4 v[118:121], v[116:117], off
	v_lshlrev_b64 v[164:165], 11, v[160:161]
	global_load_dwordx4 v[114:117], v[114:115], off
	v_lshl_add_u64 v[164:165], v[164:165], 0, v[194:195]
	s_and_b64 vcc, exec, s[4:5]
	v_lshl_add_u64 v[164:165], v[164:165], 2, s[30:31]
	s_waitcnt vmcnt(7)
	v_pk_fma_f32 v[112:113], v[112:113], v[172:173], v[176:177]
	v_pk_fma_f32 v[110:111], v[110:111], v[170:171], v[174:175]
	s_waitcnt vmcnt(6)
	v_pk_fma_f32 v[108:109], v[108:109], v[184:185], v[180:181]
	v_pk_fma_f32 v[106:107], v[106:107], v[182:183], v[178:179]
	s_cbranch_vccnz .LBB0_1389
	global_store_dwordx4 v[164:165], v[110:113], off
	global_store_dwordx4 v[164:165], v[106:109], off offset:16
	s_cbranch_execnz .LBB0_1313
.LBB0_1312:
	global_store_dwordx4 v[162:163], v[110:113], off
	global_store_dwordx4 v[166:167], v[106:109], off
.LBB0_1313:
	v_lshrrev_b32_e32 v0, 3, v160
	v_and_or_b32 v0, v0, 12, v220
	v_lshlrev_b32_e32 v161, 6, v160
	v_lshlrev_b32_e32 v160, 2, v160
	v_and_or_b32 v161, v161, s82, v221
	v_lshlrev_b32_e32 v0, 10, v0
	v_and_b32_e32 v160, 32, v160
	v_bitop3_b32 v0, v161, v0, v160 bitop3:0xde
	s_and_b64 vcc, exec, s[2:3]
	v_mov_b32_e32 v160, 0
	s_cbranch_vccnz .LBB0_1315
	v_pk_mul_f32 v[162:163], v[72:73], v[112:113]
	v_pk_mul_f32 v[160:161], v[70:71], v[110:111]
	v_pk_mul_f32 v[166:167], v[68:69], v[108:109]
	s_ashr_i32 s12, s14, 6
	v_cvt_pk_bf16_f32 v160, v160, v161
	v_cvt_pk_bf16_f32 v161, v162, v163
	v_cvt_pk_bf16_f32 v163, v166, v167
	v_add_u32_e32 v166, s12, v240
	v_ashrrev_i32_e32 v167, 31, v166
	v_lshlrev_b64 v[166:167], 15, v[166:167]
	v_pk_mul_f32 v[168:169], v[66:67], v[106:107]
	v_lshl_add_u64 v[166:167], s[52:53], 0, v[166:167]
	v_cvt_pk_bf16_f32 v162, v168, v169
	v_lshl_add_u64 v[166:167], v[166:167], 0, v[0:1]
	global_store_dwordx4 v[166:167], v[160:163], off
	s_nop 1
	v_mov_b32_e32 v161, v106
	v_mov_b32_e32 v106, v111
	v_mov_b32_e32 v111, v108
	v_mov_b32_e32 v108, v113
	v_mov_b32_e32 v160, v110
	v_pk_mul_f32 v[106:107], v[106:107], v[106:107]
	v_mov_b32_e32 v110, v112
	v_pk_mul_f32 v[108:109], v[108:109], v[108:109]
	v_pk_fma_f32 v[106:107], v[160:161], v[160:161], v[106:107]
	v_pk_fma_f32 v[108:109], v[110:111], v[110:111], v[108:109]
	s_nop 0
	v_pk_add_f32 v[106:107], v[106:107], v[108:109]
	s_nop 0
	v_add_f32_e32 v160, v106, v107
.LBB0_1315:
	s_waitcnt vmcnt(4)
	v_pk_fma_f32 v[104:105], v[104:105], v[142:143], v[136:137]
	v_pk_fma_f32 v[102:103], v[102:103], v[144:145], v[134:135]
	v_pk_fma_f32 v[100:101], v[100:101], v[140:141], v[132:133]
	s_and_b64 vcc, exec, s[4:5]
	v_pk_fma_f32 v[98:99], v[98:99], v[138:139], v[130:131]
	s_cbranch_vccnz .LBB0_1390
	global_store_dwordx4 v[164:165], v[102:105], off offset:512
	global_store_dwordx4 v[164:165], v[98:101], off offset:528
	s_cbranch_execnz .LBB0_1318
.LBB0_1317:
	global_store_dwordx4 v[156:157], v[102:105], off
	global_store_dwordx4 v[158:159], v[98:101], off
.LBB0_1318:
	s_and_b64 vcc, exec, s[2:3]
	s_cbranch_vccnz .LBB0_1322
	v_pk_mul_f32 v[106:107], v[62:63], v[102:103]
	v_pk_mul_f32 v[112:113], v[58:59], v[98:99]
	v_mul_f32_e32 v103, v103, v103
	v_mul_f32_e32 v99, v99, v99
	v_fmac_f32_e32 v103, v102, v102
	v_mul_f32_e32 v102, v105, v105
	v_fmac_f32_e32 v99, v98, v98
	v_mul_f32_e32 v98, v101, v101
	v_fmac_f32_e32 v102, v104, v104
	v_fmac_f32_e32 v98, v100, v100
	v_add_f32_e32 v102, v103, v102
	v_add_f32_e32 v98, v99, v98
	v_add_f32_e32 v98, v102, v98
	v_pk_mul_f32 v[110:111], v[60:61], v[100:101]
	v_add_f32_e32 v100, v98, v160
	v_pk_mul_f32 v[108:109], v[64:65], v[104:105]
	s_ashr_i32 s12, s14, 6
	ds_swizzle_b32 v101, v100 offset:swizzle(SWAP,16)
	v_cvt_pk_bf16_f32 v106, v106, v107
	v_cvt_pk_bf16_f32 v107, v108, v109
	v_cvt_pk_bf16_f32 v109, v110, v111
	v_add3_u32 v110, v240, s12, 2
	v_ashrrev_i32_e32 v111, 31, v110
	v_lshlrev_b64 v[98:99], 15, v[110:111]
	v_lshl_add_u64 v[98:99], s[52:53], 0, v[98:99]
	v_cvt_pk_bf16_f32 v108, v112, v113
	v_lshl_add_u64 v[98:99], v[98:99], 0, v[0:1]
	s_waitcnt lgkmcnt(0)
	v_add_f32_e32 v0, v100, v101
	global_store_dwordx4 v[98:99], v[106:109], off
	v_mov_b32_e32 v98, v0
	s_nop 1
	v_permlane32_swap_b32_e32 v0, v98
	s_and_saveexec_b64 s[12:13], s[36:37]
	s_cbranch_execz .LBB0_1321
	v_lshl_add_u64 v[100:101], v[192:193], 2, s[46:47]
	v_add_f32_e32 v0, v0, v98
	global_atomic_add_f32 v[100:101], v0, off offset:128

.LBB0_1322:
	v_lshlrev_b64 v[98:99], 11, v[150:151]
	v_lshl_add_u64 v[98:99], v[98:99], 0, v[194:195]
	s_waitcnt vmcnt(3)
	v_pk_fma_f32 v[96:97], v[96:97], v[172:173], v[128:129]
	v_pk_fma_f32 v[94:95], v[94:95], v[170:171], v[126:127]
	s_waitcnt vmcnt(2)
	v_pk_fma_f32 v[92:93], v[92:93], v[184:185], v[124:125]
	v_pk_fma_f32 v[90:91], v[90:91], v[182:183], v[122:123]
	s_and_b64 vcc, exec, s[4:5]
	v_lshl_add_u64 v[98:99], v[98:99], 2, s[30:31]
	s_cbranch_vccnz .LBB0_1391
	global_store_dwordx4 v[98:99], v[94:97], off
	global_store_dwordx4 v[98:99], v[90:93], off offset:16
	s_cbranch_execnz .LBB0_1325
.LBB0_1324:
	global_store_dwordx4 v[152:153], v[94:97], off
	global_store_dwordx4 v[154:155], v[90:93], off
.LBB0_1325:
	v_lshrrev_b32_e32 v0, 3, v150
	v_and_or_b32 v0, v0, 14, v220
	v_lshlrev_b32_e32 v100, 6, v150
	v_lshlrev_b32_e32 v101, 2, v150
	v_and_or_b32 v100, v100, s82, v221
	v_lshlrev_b32_e32 v0, 10, v0
	v_and_b32_e32 v101, 32, v101
	v_bitop3_b32 v0, v100, v0, v101 bitop3:0xde
	s_and_b64 vcc, exec, s[2:3]
	v_mov_b32_e32 v100, 0
	s_cbranch_vccnz .LBB0_1327
	v_pk_mul_f32 v[102:103], v[72:73], v[96:97]
	v_pk_mul_f32 v[100:101], v[70:71], v[94:95]
	v_pk_mul_f32 v[104:105], v[68:69], v[92:93]
	s_ashr_i32 s12, s14, 6
	v_cvt_pk_bf16_f32 v100, v100, v101
	v_cvt_pk_bf16_f32 v101, v102, v103
	v_cvt_pk_bf16_f32 v103, v104, v105
	v_add_u32_e32 v104, s12, v240
	v_ashrrev_i32_e32 v105, 31, v104
	v_lshlrev_b64 v[104:105], 15, v[104:105]
	v_pk_mul_f32 v[106:107], v[66:67], v[90:91]
	v_lshl_add_u64 v[104:105], s[52:53], 0, v[104:105]
	v_cvt_pk_bf16_f32 v102, v106, v107
	v_lshl_add_u64 v[104:105], v[104:105], 0, v[0:1]
	global_store_dwordx4 v[104:105], v[100:103], off
	s_nop 1
	v_mov_b32_e32 v101, v90
	v_mov_b32_e32 v90, v95
	v_mov_b32_e32 v95, v92
	v_mov_b32_e32 v92, v97
	v_mov_b32_e32 v100, v94
	v_pk_mul_f32 v[90:91], v[90:91], v[90:91]
	v_mov_b32_e32 v94, v96
	v_pk_mul_f32 v[92:93], v[92:93], v[92:93]
	v_pk_fma_f32 v[90:91], v[100:101], v[100:101], v[90:91]
	v_pk_fma_f32 v[92:93], v[94:95], v[94:95], v[92:93]
	s_nop 0
	v_pk_add_f32 v[90:91], v[90:91], v[92:93]
	s_nop 0
	v_add_f32_e32 v100, v90, v91
.LBB0_1327:
	s_waitcnt vmcnt(1)
	v_pk_fma_f32 v[88:89], v[88:89], v[142:143], v[120:121]
	v_pk_fma_f32 v[86:87], v[86:87], v[144:145], v[118:119]
	s_waitcnt vmcnt(0)
	v_pk_fma_f32 v[84:85], v[84:85], v[140:141], v[116:117]
	s_and_b64 vcc, exec, s[4:5]
	v_pk_fma_f32 v[82:83], v[82:83], v[138:139], v[114:115]
	s_cbranch_vccnz .LBB0_1392
	global_store_dwordx4 v[98:99], v[86:89], off offset:512
	global_store_dwordx4 v[98:99], v[82:85], off offset:528
	s_cbranch_execnz .LBB0_1330
.LBB0_1329:
	global_store_dwordx4 v[146:147], v[86:89], off
	global_store_dwordx4 v[148:149], v[82:85], off
.LBB0_1330:
	s_and_b64 vcc, exec, s[2:3]
	s_cbranch_vccnz .LBB0_1334
	v_pk_mul_f32 v[90:91], v[62:63], v[86:87]
	v_pk_mul_f32 v[96:97], v[58:59], v[82:83]
	v_mul_f32_e32 v87, v87, v87
	v_mul_f32_e32 v83, v83, v83
	v_fmac_f32_e32 v87, v86, v86
	v_mul_f32_e32 v86, v89, v89
	v_fmac_f32_e32 v83, v82, v82
	v_mul_f32_e32 v82, v85, v85
	v_fmac_f32_e32 v86, v88, v88
	v_fmac_f32_e32 v82, v84, v84
	v_add_f32_e32 v86, v87, v86
	v_add_f32_e32 v82, v83, v82
	v_add_f32_e32 v82, v86, v82
	v_pk_mul_f32 v[94:95], v[60:61], v[84:85]
	v_add_f32_e32 v84, v82, v100
	v_pk_mul_f32 v[92:93], v[64:65], v[88:89]
	s_ashr_i32 s12, s14, 6
	ds_swizzle_b32 v85, v84 offset:swizzle(SWAP,16)
	v_cvt_pk_bf16_f32 v90, v90, v91
	v_cvt_pk_bf16_f32 v91, v92, v93
	v_cvt_pk_bf16_f32 v93, v94, v95
	v_add3_u32 v94, v240, s12, 2
	v_ashrrev_i32_e32 v95, 31, v94
	v_lshlrev_b64 v[82:83], 15, v[94:95]
	v_lshl_add_u64 v[82:83], s[52:53], 0, v[82:83]
	v_cvt_pk_bf16_f32 v92, v96, v97
	v_lshl_add_u64 v[82:83], v[82:83], 0, v[0:1]
	s_waitcnt lgkmcnt(0)
	v_add_f32_e32 v0, v84, v85
	global_store_dwordx4 v[82:83], v[90:93], off
	v_mov_b32_e32 v82, v0
	s_nop 1
	v_permlane32_swap_b32_e32 v0, v82
	s_and_saveexec_b64 s[12:13], s[36:37]
	s_cbranch_execz .LBB0_1333
	v_lshl_add_u64 v[84:85], v[192:193], 2, s[46:47]
	v_add_f32_e32 v0, v0, v82
	global_atomic_add_f32 v[84:85], v0, off offset:192

.LBB0_1334:
	v_add_u32_e32 v120, 0x80, v192
	v_ashrrev_i32_e32 v121, 31, v120
	v_lshlrev_b64 v[82:83], 13, v[120:121]
	s_mov_b64 s[12:13], 0x20000
	v_lshl_add_u64 v[82:83], v[198:199], 0, v[82:83]
	v_lshl_add_u64 v[122:123], v[196:197], 0, s[12:13]
	v_cndmask_b32_e64 v85, v83, v123, s[38:39]
	v_cndmask_b32_e64 v84, v82, v122, s[38:39]
	s_mov_b64 s[12:13], 0x22000
	global_load_dwordx4 v[128:131], v[84:85], off
	v_lshl_add_u64 v[84:85], v[82:83], 0, 16
	v_lshl_add_u64 v[126:127], v[196:197], 0, s[12:13]
	s_mov_b64 s[12:13], 0x24000
	v_cndmask_b32_e64 v85, v85, v127, s[38:39]
	v_cndmask_b32_e64 v84, v84, v126, s[38:39]
	v_lshl_add_u64 v[116:117], v[196:197], 0, s[12:13]
	s_mov_b64 s[12:13], 0x26000
	global_load_dwordx4 v[132:135], v[84:85], off
	v_lshl_add_u64 v[84:85], v[82:83], 0, s[74:75]
	v_lshl_add_u64 v[82:83], v[82:83], 0, s[76:77]
	v_lshl_add_u64 v[118:119], v[196:197], 0, s[12:13]
	v_add_u32_e32 v110, 0x90, v192
	v_cndmask_b32_e64 v83, v83, v119, s[38:39]
	v_cndmask_b32_e64 v82, v82, v118, s[38:39]
	v_ashrrev_i32_e32 v111, 31, v110
	global_load_dwordx4 v[98:101], v[82:83], off
	v_lshlrev_b64 v[82:83], 13, v[110:111]
	s_mov_b64 s[12:13], 0x28000
	v_cndmask_b32_e64 v85, v85, v117, s[38:39]
	v_cndmask_b32_e64 v84, v84, v116, s[38:39]
	v_lshl_add_u64 v[82:83], v[198:199], 0, v[82:83]
	v_lshl_add_u64 v[112:113], v[196:197], 0, s[12:13]
	global_load_dwordx4 v[102:105], v[84:85], off
	v_cndmask_b32_e64 v85, v83, v113, s[38:39]
	v_cndmask_b32_e64 v84, v82, v112, s[38:39]
	s_mov_b64 s[12:13], 0x2a000
	global_load_dwordx4 v[94:97], v[84:85], off
	v_lshl_add_u64 v[84:85], v[82:83], 0, 16
	v_lshl_add_u64 v[114:115], v[196:197], 0, s[12:13]
	s_mov_b64 s[12:13], 0x2c000
	v_cndmask_b32_e64 v85, v85, v115, s[38:39]
	v_cndmask_b32_e64 v84, v84, v114, s[38:39]
	v_lshl_add_u64 v[106:107], v[196:197], 0, s[12:13]
	s_mov_b64 s[12:13], 0x2e000
	global_load_dwordx4 v[90:93], v[84:85], off
	v_lshl_add_u64 v[84:85], v[82:83], 0, s[74:75]
	v_lshl_add_u64 v[82:83], v[82:83], 0, s[76:77]
	v_lshl_add_u64 v[108:109], v[196:197], 0, s[12:13]
	v_cndmask_b32_e64 v85, v85, v107, s[38:39]
	v_cndmask_b32_e64 v84, v84, v106, s[38:39]
	v_cndmask_b32_e64 v83, v83, v109, s[38:39]
	v_cndmask_b32_e64 v82, v82, v108, s[38:39]
	global_load_dwordx4 v[86:89], v[84:85], off
	v_lshlrev_b64 v[124:125], 11, v[120:121]
	global_load_dwordx4 v[82:85], v[82:83], off
	v_lshl_add_u64 v[124:125], v[124:125], 0, v[194:195]
	s_and_b64 vcc, exec, s[4:5]
	v_lshl_add_u64 v[124:125], v[124:125], 2, s[30:31]
	s_waitcnt vmcnt(7)
	v_pk_fma_f32 v[80:81], v[80:81], v[172:173], v[130:131]
	v_pk_fma_f32 v[78:79], v[78:79], v[170:171], v[128:129]
	s_waitcnt vmcnt(6)
	v_pk_fma_f32 v[76:77], v[76:77], v[184:185], v[134:135]
	v_pk_fma_f32 v[74:75], v[74:75], v[182:183], v[132:133]
	s_cbranch_vccnz .LBB0_1393
	global_store_dwordx4 v[124:125], v[78:81], off
	global_store_dwordx4 v[124:125], v[74:77], off offset:16
	s_cbranch_execnz .LBB0_1337
.LBB0_1336:
	global_store_dwordx4 v[122:123], v[78:81], off
	global_store_dwordx4 v[126:127], v[74:77], off
.LBB0_1337:
	v_ashrrev_i32_e32 v0, 3, v120
	v_and_b32_e32 v122, 0xffffffe0, v0
	v_lshlrev_b32_e32 v0, 7, v120
	v_lshlrev_b32_e32 v121, 6, v120
	v_lshlrev_b32_e32 v120, 2, v120
	v_and_or_b32 v121, v121, s82, v221
	v_and_b32_e32 v120, 32, v120
	v_and_b32_e32 v0, 0x4000, v0
	v_bitop3_b32 v120, v121, v226, v120 bitop3:0xde
	v_mov_b32_e32 v121, v1
	s_and_b64 vcc, exec, s[2:3]
	v_mov_b32_e32 v123, 0
	s_cbranch_vccnz .LBB0_1339
	v_pk_mul_f32 v[128:129], v[72:73], v[80:81]
	v_pk_mul_f32 v[126:127], v[70:71], v[78:79]
	v_pk_mul_f32 v[130:131], v[68:69], v[76:77]
	s_ashr_i32 s12, s14, 6
	v_cvt_pk_bf16_f32 v126, v126, v127
	v_cvt_pk_bf16_f32 v127, v128, v129
	v_cvt_pk_bf16_f32 v129, v130, v131
	v_add_u32_e32 v130, s12, v122
	v_ashrrev_i32_e32 v131, 31, v130
	v_lshlrev_b64 v[130:131], 15, v[130:131]
	v_lshl_add_u64 v[130:131], s[44:45], 0, v[130:131]
	v_pk_mul_f32 v[132:133], v[66:67], v[74:75]
	v_lshl_add_u64 v[130:131], v[130:131], 0, v[0:1]
	v_cvt_pk_bf16_f32 v128, v132, v133
	v_lshl_add_u64 v[130:131], v[130:131], 0, v[120:121]
	global_store_dwordx4 v[130:131], v[126:129], off
	s_nop 1
	v_mov_b32_e32 v127, v74
	v_mov_b32_e32 v74, v79
	v_mov_b32_e32 v79, v76
	v_mov_b32_e32 v76, v81
	v_mov_b32_e32 v126, v78
	v_pk_mul_f32 v[74:75], v[74:75], v[74:75]
	v_mov_b32_e32 v78, v80
	v_pk_mul_f32 v[76:77], v[76:77], v[76:77]
	v_pk_fma_f32 v[74:75], v[126:127], v[126:127], v[74:75]
	v_pk_fma_f32 v[76:77], v[78:79], v[78:79], v[76:77]
	s_nop 0
	v_pk_add_f32 v[74:75], v[74:75], v[76:77]
	s_nop 0
	v_add_f32_e32 v123, v74, v75
.LBB0_1339:
	s_waitcnt vmcnt(4)
	v_pk_fma_f32 v[56:57], v[56:57], v[142:143], v[104:105]
	v_pk_fma_f32 v[54:55], v[54:55], v[144:145], v[102:103]
	v_pk_fma_f32 v[52:53], v[52:53], v[140:141], v[100:101]
	s_and_b64 vcc, exec, s[4:5]
	v_pk_fma_f32 v[50:51], v[50:51], v[138:139], v[98:99]
	s_cbranch_vccnz .LBB0_1394
	global_store_dwordx4 v[124:125], v[54:57], off offset:512
	global_store_dwordx4 v[124:125], v[50:53], off offset:528
	s_cbranch_execnz .LBB0_1342
.LBB0_1341:
	global_store_dwordx4 v[116:117], v[54:57], off
	global_store_dwordx4 v[118:119], v[50:53], off
.LBB0_1342:
	s_and_b64 vcc, exec, s[2:3]
	s_cbranch_vccnz .LBB0_1346
	v_pk_mul_f32 v[74:75], v[62:63], v[54:55]
	v_pk_mul_f32 v[80:81], v[58:59], v[50:51]
	v_mul_f32_e32 v55, v55, v55
	v_mul_f32_e32 v51, v51, v51
	v_fmac_f32_e32 v55, v54, v54
	v_mul_f32_e32 v54, v57, v57
	v_fmac_f32_e32 v51, v50, v50
	v_mul_f32_e32 v50, v53, v53
	v_fmac_f32_e32 v54, v56, v56
	v_fmac_f32_e32 v50, v52, v52
	v_add_f32_e32 v54, v55, v54
	v_add_f32_e32 v50, v51, v50
	v_add_f32_e32 v50, v54, v50
	v_pk_mul_f32 v[76:77], v[64:65], v[56:57]
	v_pk_mul_f32 v[78:79], v[60:61], v[52:53]
	s_ashr_i32 s12, s14, 6
	v_add_f32_e32 v52, v50, v123
	v_cvt_pk_bf16_f32 v74, v74, v75
	v_cvt_pk_bf16_f32 v75, v76, v77
	v_cvt_pk_bf16_f32 v77, v78, v79
	v_add3_u32 v78, v122, s12, 2
	ds_swizzle_b32 v53, v52 offset:swizzle(SWAP,16)
	v_ashrrev_i32_e32 v79, 31, v78
	v_lshlrev_b64 v[78:79], 15, v[78:79]
	v_lshl_add_u64 v[50:51], s[44:45], 0, v[78:79]
	v_lshl_add_u64 v[50:51], v[50:51], 0, v[0:1]
	v_cvt_pk_bf16_f32 v76, v80, v81
	v_lshl_add_u64 v[50:51], v[50:51], 0, v[120:121]
	s_waitcnt lgkmcnt(0)
	v_add_f32_e32 v0, v52, v53
	global_store_dwordx4 v[50:51], v[74:77], off
	v_mov_b32_e32 v50, v0
	s_nop 1
	v_permlane32_swap_b32_e32 v0, v50
	s_and_saveexec_b64 s[12:13], s[36:37]
	s_cbranch_execz .LBB0_1345
	v_lshl_add_u64 v[52:53], v[192:193], 2, s[46:47]
	v_add_f32_e32 v0, v0, v50
	global_atomic_add_f32 v[52:53], v0, off offset:512

.LBB0_1346:
	v_lshlrev_b64 v[50:51], 11, v[110:111]
	v_lshl_add_u64 v[50:51], v[50:51], 0, v[194:195]
	s_waitcnt vmcnt(3)
	v_pk_fma_f32 v[48:49], v[48:49], v[172:173], v[96:97]
	v_pk_fma_f32 v[46:47], v[46:47], v[170:171], v[94:95]
	s_waitcnt vmcnt(2)
	v_pk_fma_f32 v[44:45], v[44:45], v[184:185], v[92:93]
	v_pk_fma_f32 v[42:43], v[42:43], v[182:183], v[90:91]
	s_and_b64 vcc, exec, s[4:5]
	v_lshl_add_u64 v[52:53], v[50:51], 2, s[30:31]
	s_cbranch_vccnz .LBB0_1395
	global_store_dwordx4 v[52:53], v[46:49], off
	global_store_dwordx4 v[52:53], v[42:45], off offset:16
	s_cbranch_execnz .LBB0_1349
.LBB0_1348:
	global_store_dwordx4 v[112:113], v[46:49], off
	global_store_dwordx4 v[114:115], v[42:45], off
.LBB0_1349:
	v_lshrrev_b32_e32 v50, 3, v110
	v_ashrrev_i32_e32 v0, 3, v110
	v_and_or_b32 v50, v50, 10, v220
	v_lshlrev_b32_e32 v51, 6, v110
	v_lshlrev_b32_e32 v55, 2, v110
	v_and_b32_e32 v54, 0xffffffe0, v0
	v_lshlrev_b32_e32 v0, 7, v110
	v_and_or_b32 v51, v51, s82, v221
	v_lshlrev_b32_e32 v50, 10, v50
	v_and_b32_e32 v55, 32, v55
	v_and_b32_e32 v0, 0x4000, v0
	v_bitop3_b32 v50, v51, v50, v55 bitop3:0xde
	v_mov_b32_e32 v51, v1
	s_and_b64 vcc, exec, s[2:3]
	v_mov_b32_e32 v55, 0
	s_cbranch_vccnz .LBB0_1351
	v_pk_mul_f32 v[56:57], v[72:73], v[48:49]
	v_pk_mul_f32 v[74:75], v[70:71], v[46:47]
	s_ashr_i32 s12, s14, 6
	v_cvt_pk_bf16_f32 v74, v74, v75
	v_cvt_pk_bf16_f32 v75, v56, v57
	v_add_u32_e32 v56, s12, v54
	v_ashrrev_i32_e32 v57, 31, v56
	v_lshlrev_b64 v[56:57], 15, v[56:57]
	v_lshl_add_u64 v[56:57], s[44:45], 0, v[56:57]
	v_pk_mul_f32 v[78:79], v[68:69], v[44:45]
	v_pk_mul_f32 v[76:77], v[66:67], v[42:43]
	v_lshl_add_u64 v[56:57], v[56:57], 0, v[0:1]
	v_cvt_pk_bf16_f32 v76, v76, v77
	v_cvt_pk_bf16_f32 v77, v78, v79
	v_lshl_add_u64 v[56:57], v[56:57], 0, v[50:51]
	global_store_dwordx4 v[56:57], v[74:77], off
	v_mov_b32_e32 v57, v42
	v_mov_b32_e32 v42, v47
	v_mov_b32_e32 v47, v44
	v_mov_b32_e32 v44, v49
	v_mov_b32_e32 v56, v46
	v_pk_mul_f32 v[42:43], v[42:43], v[42:43]
	v_mov_b32_e32 v46, v48
	v_pk_mul_f32 v[44:45], v[44:45], v[44:45]
	v_pk_fma_f32 v[42:43], v[56:57], v[56:57], v[42:43]
	v_pk_fma_f32 v[44:45], v[46:47], v[46:47], v[44:45]
	s_nop 0
	v_pk_add_f32 v[42:43], v[42:43], v[44:45]
	s_nop 0
	v_add_f32_e32 v55, v42, v43
.LBB0_1351:
	s_waitcnt vmcnt(1)
	v_pk_fma_f32 v[40:41], v[40:41], v[142:143], v[88:89]
	v_pk_fma_f32 v[38:39], v[38:39], v[144:145], v[86:87]
	s_waitcnt vmcnt(0)
	v_pk_fma_f32 v[36:37], v[36:37], v[140:141], v[84:85]
	s_and_b64 vcc, exec, s[4:5]
	v_pk_fma_f32 v[34:35], v[34:35], v[138:139], v[82:83]
	s_cbranch_vccnz .LBB0_1396
	global_store_dwordx4 v[52:53], v[38:41], off offset:512
	global_store_dwordx4 v[52:53], v[34:37], off offset:528
	s_cbranch_execnz .LBB0_1354
.LBB0_1353:
	global_store_dwordx4 v[106:107], v[38:41], off
	global_store_dwordx4 v[108:109], v[34:37], off
.LBB0_1354:
	s_and_b64 vcc, exec, s[2:3]
	s_cbranch_vccnz .LBB0_1358
	v_pk_mul_f32 v[42:43], v[62:63], v[38:39]
	v_pk_mul_f32 v[48:49], v[58:59], v[34:35]
	v_mul_f32_e32 v39, v39, v39
	v_mul_f32_e32 v35, v35, v35
	v_fmac_f32_e32 v39, v38, v38
	v_mul_f32_e32 v38, v41, v41
	v_fmac_f32_e32 v35, v34, v34
	v_mul_f32_e32 v34, v37, v37
	v_fmac_f32_e32 v38, v40, v40
	v_fmac_f32_e32 v34, v36, v36
	v_add_f32_e32 v38, v39, v38
	v_add_f32_e32 v34, v35, v34
	v_add_f32_e32 v34, v38, v34
	v_pk_mul_f32 v[44:45], v[64:65], v[40:41]
	v_pk_mul_f32 v[46:47], v[60:61], v[36:37]
	s_ashr_i32 s12, s14, 6
	v_add_f32_e32 v36, v34, v55
	v_cvt_pk_bf16_f32 v42, v42, v43
	v_cvt_pk_bf16_f32 v43, v44, v45
	v_cvt_pk_bf16_f32 v45, v46, v47
	v_add3_u32 v46, v54, s12, 2
	ds_swizzle_b32 v37, v36 offset:swizzle(SWAP,16)
	v_ashrrev_i32_e32 v47, 31, v46
	v_lshlrev_b64 v[46:47], 15, v[46:47]
	v_lshl_add_u64 v[34:35], s[44:45], 0, v[46:47]
	v_lshl_add_u64 v[34:35], v[34:35], 0, v[0:1]
	v_cvt_pk_bf16_f32 v44, v48, v49
	v_lshl_add_u64 v[34:35], v[34:35], 0, v[50:51]
	s_waitcnt lgkmcnt(0)
	v_add_f32_e32 v0, v36, v37
	global_store_dwordx4 v[34:35], v[42:45], off
	v_mov_b32_e32 v34, v0
	s_nop 1
	v_permlane32_swap_b32_e32 v0, v34
	s_and_saveexec_b64 s[12:13], s[36:37]
	s_cbranch_execz .LBB0_1357
	v_lshl_add_u64 v[36:37], v[192:193], 2, s[46:47]
	v_add_f32_e32 v0, v0, v34
	global_atomic_add_f32 v[36:37], v0, off offset:576

.LBB0_1358:
	v_add_u32_e32 v88, 0xa0, v192
	v_ashrrev_i32_e32 v89, 31, v88
	v_lshlrev_b64 v[34:35], 13, v[88:89]
	s_mov_b64 s[12:13], 0x30000
	v_lshl_add_u64 v[34:35], v[198:199], 0, v[34:35]
	v_lshl_add_u64 v[92:93], v[196:197], 0, s[12:13]
	v_cndmask_b32_e64 v37, v35, v93, s[38:39]
	v_cndmask_b32_e64 v36, v34, v92, s[38:39]
	s_mov_b64 s[12:13], 0x32000
	global_load_dwordx4 v[96:99], v[36:37], off
	v_lshl_add_u64 v[36:37], v[34:35], 0, 16
	v_lshl_add_u64 v[94:95], v[196:197], 0, s[12:13]
	s_mov_b64 s[12:13], 0x34000
	v_cndmask_b32_e64 v37, v37, v95, s[38:39]
	v_cndmask_b32_e64 v36, v36, v94, s[38:39]
	v_lshl_add_u64 v[84:85], v[196:197], 0, s[12:13]
	s_mov_b64 s[12:13], 0x36000
	global_load_dwordx4 v[100:103], v[36:37], off
	v_lshl_add_u64 v[36:37], v[34:35], 0, s[74:75]
	v_lshl_add_u64 v[34:35], v[34:35], 0, s[76:77]
	v_lshl_add_u64 v[86:87], v[196:197], 0, s[12:13]
	v_add_u32_e32 v78, 0xb0, v192
	v_cndmask_b32_e64 v35, v35, v87, s[38:39]
	v_cndmask_b32_e64 v34, v34, v86, s[38:39]
	v_ashrrev_i32_e32 v79, 31, v78
	global_load_dwordx4 v[50:53], v[34:35], off
	v_lshlrev_b64 v[34:35], 13, v[78:79]
	s_mov_b64 s[12:13], 0x38000
	v_cndmask_b32_e64 v37, v37, v85, s[38:39]
	v_cndmask_b32_e64 v36, v36, v84, s[38:39]
	v_lshl_add_u64 v[34:35], v[198:199], 0, v[34:35]
	v_lshl_add_u64 v[80:81], v[196:197], 0, s[12:13]
	global_load_dwordx4 v[54:57], v[36:37], off
	v_cndmask_b32_e64 v37, v35, v81, s[38:39]
	v_cndmask_b32_e64 v36, v34, v80, s[38:39]
	s_mov_b64 s[12:13], 0x3a000
	global_load_dwordx4 v[46:49], v[36:37], off
	v_lshl_add_u64 v[36:37], v[34:35], 0, 16
	v_lshl_add_u64 v[82:83], v[196:197], 0, s[12:13]
	s_mov_b64 s[12:13], 0x3c000
	v_cndmask_b32_e64 v37, v37, v83, s[38:39]
	v_cndmask_b32_e64 v36, v36, v82, s[38:39]
	v_lshl_add_u64 v[74:75], v[196:197], 0, s[12:13]
	s_mov_b64 s[12:13], 0x3e000
	global_load_dwordx4 v[42:45], v[36:37], off
	v_lshl_add_u64 v[36:37], v[34:35], 0, s[74:75]
	v_lshl_add_u64 v[34:35], v[34:35], 0, s[76:77]
	v_lshl_add_u64 v[76:77], v[196:197], 0, s[12:13]
	v_cndmask_b32_e64 v37, v37, v75, s[38:39]
	v_cndmask_b32_e64 v36, v36, v74, s[38:39]
	v_cndmask_b32_e64 v35, v35, v77, s[38:39]
	v_cndmask_b32_e64 v34, v34, v76, s[38:39]
	global_load_dwordx4 v[38:41], v[36:37], off
	v_lshlrev_b64 v[90:91], 11, v[88:89]
	global_load_dwordx4 v[34:37], v[34:35], off
	v_lshl_add_u64 v[90:91], v[90:91], 0, v[194:195]
	s_and_b64 vcc, exec, s[4:5]
	v_lshl_add_u64 v[90:91], v[90:91], 2, s[30:31]
	s_waitcnt vmcnt(7)
	v_pk_fma_f32 v[32:33], v[32:33], v[172:173], v[98:99]
	v_pk_fma_f32 v[30:31], v[30:31], v[170:171], v[96:97]
	s_waitcnt vmcnt(6)
	v_pk_fma_f32 v[28:29], v[28:29], v[184:185], v[102:103]
	v_pk_fma_f32 v[26:27], v[26:27], v[182:183], v[100:101]
	s_cbranch_vccnz .LBB0_1397
	global_store_dwordx4 v[90:91], v[30:33], off
	global_store_dwordx4 v[90:91], v[26:29], off offset:16
	s_cbranch_execnz .LBB0_1361
.LBB0_1360:
	global_store_dwordx4 v[92:93], v[30:33], off
	global_store_dwordx4 v[94:95], v[26:29], off
.LBB0_1361:
	v_ashrrev_i32_e32 v0, 3, v88
	v_lshrrev_b32_e32 v89, 3, v88
	v_and_b32_e32 v92, 0xffffffe0, v0
	v_lshlrev_b32_e32 v0, 7, v88
	v_and_or_b32 v89, v89, 12, v220
	v_lshlrev_b32_e32 v93, 6, v88
	v_lshlrev_b32_e32 v88, 2, v88
	v_and_or_b32 v93, v93, s82, v221
	v_lshlrev_b32_e32 v89, 10, v89
	v_and_b32_e32 v88, 32, v88
	v_and_b32_e32 v0, 0x4000, v0
	v_bitop3_b32 v88, v93, v89, v88 bitop3:0xde
	v_mov_b32_e32 v89, v1
	s_and_b64 vcc, exec, s[2:3]
	v_mov_b32_e32 v93, 0
	s_cbranch_vccnz .LBB0_1363
	v_pk_mul_f32 v[96:97], v[72:73], v[32:33]
	v_pk_mul_f32 v[94:95], v[70:71], v[30:31]
	v_pk_mul_f32 v[98:99], v[68:69], v[28:29]
	s_ashr_i32 s12, s14, 6
	v_cvt_pk_bf16_f32 v94, v94, v95
	v_cvt_pk_bf16_f32 v95, v96, v97
	v_cvt_pk_bf16_f32 v97, v98, v99
	v_add_u32_e32 v98, s12, v92
	v_ashrrev_i32_e32 v99, 31, v98
	v_lshlrev_b64 v[98:99], 15, v[98:99]
	v_lshl_add_u64 v[98:99], s[44:45], 0, v[98:99]
	v_pk_mul_f32 v[100:101], v[66:67], v[26:27]
	v_lshl_add_u64 v[98:99], v[98:99], 0, v[0:1]
	v_cvt_pk_bf16_f32 v96, v100, v101
	v_lshl_add_u64 v[98:99], v[98:99], 0, v[88:89]
	global_store_dwordx4 v[98:99], v[94:97], off
	s_nop 1
	v_mov_b32_e32 v95, v26
	v_mov_b32_e32 v26, v31
	v_mov_b32_e32 v31, v28
	v_mov_b32_e32 v28, v33
	v_mov_b32_e32 v94, v30
	v_pk_mul_f32 v[26:27], v[26:27], v[26:27]
	v_mov_b32_e32 v30, v32
	v_pk_mul_f32 v[28:29], v[28:29], v[28:29]
	v_pk_fma_f32 v[26:27], v[94:95], v[94:95], v[26:27]
	v_pk_fma_f32 v[28:29], v[30:31], v[30:31], v[28:29]
	s_nop 0
	v_pk_add_f32 v[26:27], v[26:27], v[28:29]
	s_nop 0
	v_add_f32_e32 v93, v26, v27
.LBB0_1363:
	s_waitcnt vmcnt(4)
	v_pk_fma_f32 v[24:25], v[24:25], v[142:143], v[56:57]
	v_pk_fma_f32 v[22:23], v[22:23], v[144:145], v[54:55]
	v_pk_fma_f32 v[20:21], v[20:21], v[140:141], v[52:53]
	s_and_b64 vcc, exec, s[4:5]
	v_pk_fma_f32 v[18:19], v[18:19], v[138:139], v[50:51]
	s_cbranch_vccnz .LBB0_1398
	global_store_dwordx4 v[90:91], v[22:25], off offset:512
	global_store_dwordx4 v[90:91], v[18:21], off offset:528
	s_cbranch_execnz .LBB0_1366
.LBB0_1365:
	global_store_dwordx4 v[84:85], v[22:25], off
	global_store_dwordx4 v[86:87], v[18:21], off
.LBB0_1366:
	s_and_b64 vcc, exec, s[2:3]
	s_cbranch_vccnz .LBB0_1370
	v_pk_mul_f32 v[26:27], v[62:63], v[22:23]
	v_pk_mul_f32 v[32:33], v[58:59], v[18:19]
	v_mul_f32_e32 v23, v23, v23
	v_mul_f32_e32 v19, v19, v19
	v_fmac_f32_e32 v23, v22, v22
	v_mul_f32_e32 v22, v25, v25
	v_fmac_f32_e32 v19, v18, v18
	v_mul_f32_e32 v18, v21, v21
	v_fmac_f32_e32 v22, v24, v24
	v_fmac_f32_e32 v18, v20, v20
	v_add_f32_e32 v22, v23, v22
	v_add_f32_e32 v18, v19, v18
	v_add_f32_e32 v18, v22, v18
	v_pk_mul_f32 v[28:29], v[64:65], v[24:25]
	v_pk_mul_f32 v[30:31], v[60:61], v[20:21]
	s_ashr_i32 s12, s14, 6
	v_add_f32_e32 v20, v18, v93
	v_cvt_pk_bf16_f32 v26, v26, v27
	v_cvt_pk_bf16_f32 v27, v28, v29
	v_cvt_pk_bf16_f32 v29, v30, v31
	v_add3_u32 v30, v92, s12, 2
	ds_swizzle_b32 v21, v20 offset:swizzle(SWAP,16)
	v_ashrrev_i32_e32 v31, 31, v30
	v_lshlrev_b64 v[30:31], 15, v[30:31]
	v_lshl_add_u64 v[18:19], s[44:45], 0, v[30:31]
	v_lshl_add_u64 v[18:19], v[18:19], 0, v[0:1]
	v_cvt_pk_bf16_f32 v28, v32, v33
	v_lshl_add_u64 v[18:19], v[18:19], 0, v[88:89]
	s_waitcnt lgkmcnt(0)
	v_add_f32_e32 v0, v20, v21
	global_store_dwordx4 v[18:19], v[26:29], off
	v_mov_b32_e32 v18, v0
	s_nop 1
	v_permlane32_swap_b32_e32 v0, v18
	s_and_saveexec_b64 s[12:13], s[36:37]
	s_cbranch_execz .LBB0_1369
	v_lshl_add_u64 v[20:21], v[192:193], 2, s[46:47]
	v_add_f32_e32 v0, v0, v18
	global_atomic_add_f32 v[20:21], v0, off offset:640

.LBB0_1370:
	v_lshlrev_b64 v[18:19], 11, v[78:79]
	v_lshl_add_u64 v[18:19], v[18:19], 0, v[194:195]
	s_waitcnt vmcnt(3)
	v_pk_fma_f32 v[16:17], v[16:17], v[172:173], v[48:49]
	v_pk_fma_f32 v[14:15], v[14:15], v[170:171], v[46:47]
	s_waitcnt vmcnt(2)
	v_pk_fma_f32 v[12:13], v[12:13], v[184:185], v[44:45]
	v_pk_fma_f32 v[10:11], v[10:11], v[182:183], v[42:43]
	s_and_b64 vcc, exec, s[4:5]
	v_lshl_add_u64 v[20:21], v[18:19], 2, s[30:31]
	s_cbranch_vccnz .LBB0_1399
	global_store_dwordx4 v[20:21], v[14:17], off
	global_store_dwordx4 v[20:21], v[10:13], off offset:16
	s_cbranch_execnz .LBB0_1373
.LBB0_1372:
	global_store_dwordx4 v[80:81], v[14:17], off
	global_store_dwordx4 v[82:83], v[10:13], off
.LBB0_1373:
	v_lshrrev_b32_e32 v18, 3, v78
	v_ashrrev_i32_e32 v0, 3, v78
	v_and_or_b32 v18, v18, 14, v220
	v_lshlrev_b32_e32 v19, 6, v78
	v_lshlrev_b32_e32 v23, 2, v78
	v_and_b32_e32 v22, 0xffffffe0, v0
	v_lshlrev_b32_e32 v0, 7, v78
	v_and_or_b32 v19, v19, s82, v221
	v_lshlrev_b32_e32 v18, 10, v18
	v_and_b32_e32 v23, 32, v23
	v_and_b32_e32 v0, 0x4000, v0
	v_bitop3_b32 v18, v19, v18, v23 bitop3:0xde
	v_mov_b32_e32 v19, v1
	s_and_b64 vcc, exec, s[2:3]
	v_mov_b32_e32 v23, 0
	s_cbranch_vccnz .LBB0_1375
	v_pk_mul_f32 v[26:27], v[72:73], v[16:17]
	v_pk_mul_f32 v[24:25], v[70:71], v[14:15]
	v_pk_mul_f32 v[28:29], v[68:69], v[12:13]
	s_ashr_i32 s12, s14, 6
	v_cvt_pk_bf16_f32 v24, v24, v25
	v_cvt_pk_bf16_f32 v25, v26, v27
	v_cvt_pk_bf16_f32 v27, v28, v29
	v_add_u32_e32 v28, s12, v22
	v_ashrrev_i32_e32 v29, 31, v28
	v_lshlrev_b64 v[28:29], 15, v[28:29]
	v_lshl_add_u64 v[28:29], s[44:45], 0, v[28:29]
	v_pk_mul_f32 v[30:31], v[66:67], v[10:11]
	v_lshl_add_u64 v[28:29], v[28:29], 0, v[0:1]
	v_cvt_pk_bf16_f32 v26, v30, v31
	v_lshl_add_u64 v[28:29], v[28:29], 0, v[18:19]
	global_store_dwordx4 v[28:29], v[24:27], off
	s_nop 1
	v_mov_b32_e32 v25, v10
	v_mov_b32_e32 v10, v15
	v_mov_b32_e32 v15, v12
	v_mov_b32_e32 v12, v17
	v_mov_b32_e32 v24, v14
	v_pk_mul_f32 v[10:11], v[10:11], v[10:11]
	v_mov_b32_e32 v14, v16
	v_pk_mul_f32 v[12:13], v[12:13], v[12:13]
	v_pk_fma_f32 v[10:11], v[24:25], v[24:25], v[10:11]
	v_pk_fma_f32 v[12:13], v[14:15], v[14:15], v[12:13]
	s_nop 0
	v_pk_add_f32 v[10:11], v[10:11], v[12:13]
	s_nop 0
	v_add_f32_e32 v23, v10, v11
.LBB0_1375:
	s_waitcnt vmcnt(1)
	v_pk_fma_f32 v[8:9], v[8:9], v[142:143], v[40:41]
	v_pk_fma_f32 v[6:7], v[6:7], v[144:145], v[38:39]
	s_waitcnt vmcnt(0)
	v_pk_fma_f32 v[4:5], v[4:5], v[140:141], v[36:37]
	s_and_b64 vcc, exec, s[4:5]
	v_pk_fma_f32 v[2:3], v[2:3], v[138:139], v[34:35]
	s_cbranch_vccnz .LBB0_1400
	global_store_dwordx4 v[20:21], v[6:9], off offset:512
	global_store_dwordx4 v[20:21], v[2:5], off offset:528
	s_cbranch_execnz .LBB0_1378
.LBB0_1377:
	global_store_dwordx4 v[74:75], v[6:9], off
	global_store_dwordx4 v[76:77], v[2:5], off
.LBB0_1378:
	s_and_b64 vcc, exec, s[2:3]
	s_cbranch_vccnz .LBB0_1382
	v_pk_mul_f32 v[10:11], v[62:63], v[6:7]
	v_pk_mul_f32 v[16:17], v[58:59], v[2:3]
	v_mul_f32_e32 v7, v7, v7
	v_mul_f32_e32 v3, v3, v3
	v_fmac_f32_e32 v7, v6, v6
	v_mul_f32_e32 v6, v9, v9
	v_fmac_f32_e32 v3, v2, v2
	v_mul_f32_e32 v2, v5, v5
	v_fmac_f32_e32 v6, v8, v8
	v_fmac_f32_e32 v2, v4, v4
	v_add_f32_e32 v6, v7, v6
	v_add_f32_e32 v2, v3, v2
	v_add_f32_e32 v2, v6, v2
	v_pk_mul_f32 v[12:13], v[64:65], v[8:9]
	v_pk_mul_f32 v[14:15], v[60:61], v[4:5]
	s_ashr_i32 s2, s14, 6
	v_add_f32_e32 v4, v2, v23
	v_cvt_pk_bf16_f32 v10, v10, v11
	v_cvt_pk_bf16_f32 v11, v12, v13
	v_cvt_pk_bf16_f32 v13, v14, v15
	v_add3_u32 v14, v22, s2, 2
	ds_swizzle_b32 v5, v4 offset:swizzle(SWAP,16)
	v_ashrrev_i32_e32 v15, 31, v14
	v_lshlrev_b64 v[14:15], 15, v[14:15]
	v_lshl_add_u64 v[2:3], s[44:45], 0, v[14:15]
	v_lshl_add_u64 v[2:3], v[2:3], 0, v[0:1]
	v_cvt_pk_bf16_f32 v12, v16, v17
	v_lshl_add_u64 v[2:3], v[2:3], 0, v[18:19]
	s_waitcnt lgkmcnt(0)
	v_add_f32_e32 v0, v4, v5
	global_store_dwordx4 v[2:3], v[10:13], off
	v_mov_b32_e32 v2, v0
	s_nop 1
	v_permlane32_swap_b32_e32 v0, v2
	s_and_saveexec_b64 s[2:3], s[36:37]
	s_cbranch_execz .LBB0_1381
	v_lshl_add_u64 v[4:5], v[192:193], 2, s[46:47]
	v_add_f32_e32 v0, v0, v2
	global_atomic_add_f32 v[4:5], v0, off offset:704
